# speedup vs baseline: 1.0303x; 1.0141x over previous
; #define SBAR() __builtin_amdgcn_sched_barrier(0)
; __device__ __forceinline__ int opq(int x) { asm volatile("" : "+v"(x)); return x; }
; __device__ __forceinline__ int v_st(int k, int c) { const int kk = (k & ~0xC) | ((k & 4) << 1) | ((k & 8) >> 1); return ((kk >> 3) * 4 + (c >> 5)) * 512 + ((kk & 7) * 32 + (c & 31)) * 2; }
; __device__ __forceinline__ int v_rd_base(int lane) { return ((lane & 3) << 3) | (((lane >> 2) & 3) << 6) | (((lane >> 4) & 1) << 5) | (((lane >> 5) & 1) << 8); }
; #define SLOAD(S, k0) do { vs##S##0 = *reinterpret_cast<const bf16x8*>(&Vh[(size_t)((k0) + sr) * LDK + sc]); \
;     vs##S##1 = *reinterpret_cast<const bf16x8*>(&Vh[(size_t)((k0) + 32 + sr) * LDK + sc]); \
;     ks##S = *reinterpret_cast<const bf16x8*>(&Kh[(size_t)((k0) + kr) * LDK + kc]); } while (0)
; __device__ __forceinline__ void attn_stream(const u16* __restrict__ Qb, const u16* __restrict__ Kh, const u16* __restrict__ Vh,
;                                             int seq, char* lds, f32x16 (&o)[4]) {
;     ...
;   const int tid = opq((int)threadIdx.x), wid = tid >> 6, lane = tid & 63, r32 = lane & 31, hi = lane >> 5;
;   char* V_lds = lds; char* K_lds = lds + 3 * SHM_V;
;   float* wsl = (float*)(lds + 3 * SHM_V + 3 * SHM_K) + wid * 64; float* li_l = wsl; float* al_l = wsl + 32;
;   float m_reg = 0.f, l_reg = 0.f; bf16x8 qr[4]; f32x16 negm = {};
; #pragma unroll
;   for (int d = 0; d < 4; ++d) o[d] = f32x16{};
;   const u16* Qw = Qb + (size_t)(wid * 32 + r32) * LDQ + hi * 8;
; #pragma unroll
;   for (int d0 = 0; d0 < 4; ++d0) qr[d0] = *reinterpret_cast<const bf16x8*>(Qw + d0 * 16);
;   const int sr = tid >> 4, sc = (tid & 15) * 8, vst0 = v_st(sr, sc), vst1 = v_st(32 + sr, sc);
;   const int kr = tid >> 3, kc = (tid & 7) * 8, kst = KSWZ(kr, kc * 2);
;   const int vb0 = (int)(uintptr_t)(__attribute__((address_space(3))) char*)V_lds + v_rd_base(lane);
;   bf16x8 vsA0, vsA1, ksA, vsB0, vsB1, ksB;
;     ...
;   f32x16 p0, p1; float al; bf16x8 pa0, pa1, pa2, pa3; const int NT = seq / 64;
;     ...
;   const bool late = wid >= 4;
;   __syncthreads();
;   SLOAD(A, 0); SLOAD(B, 64); asm volatile("s_waitcnt vmcnt(0)" ::: "memory"); SWRITE(0, A); SWRITE(1, B);
;   SLOAD(A, 128); SLOAD(B, 192);
;   __syncthreads();
;   qkt(p0, p1, K_lds, qr, r32, hi, negm); SOFTMAX(true); SBAR();
;   if (late) __syncthreads();
;   int t3 = 0;
.LBB0_330:
	s_or_b64 exec, exec, s[4:5]
	v_lshlrev_b32_e32 v19, 4, v43
	v_lshlrev_b32_e32 v18, 3, v43
	v_and_b32_e32 v19, 0xc0, v19
	v_lshlrev_b32_e32 v20, 1, v43
	v_and_or_b32 v19, v18, 24, v19
	v_and_b32_e32 v20, 32, v20
	v_and_b32_e32 v18, 0x100, v18
	v_or3_b32 v18, v19, v20, v18
	v_and_b32_e32 v20, 15, v40
	v_add_u32_e32 v213, 0, v18
	v_mad_i64_i32 v[18:19], s[42:43], s6, v202, v[34:35]
	v_lshlrev_b32_e32 v20, 4, v20
	v_mov_b32_e32 v21, v191
	v_lshl_add_u64 v[18:19], v[18:19], 0, v[20:21]
	v_and_b32_e32 v20, 7, v40
	s_lshl_b32 s5, s3, 1
	s_mul_hi_i32 s57, s6, 0x880000
	s_mul_i32 s56, s6, 0x880000
	v_lshl_add_u64 v[194:195], s[26:27], 0, v[18:19]
	v_mad_i64_i32 v[18:19], s[6:7], s6, v202, v[36:37]
	v_lshlrev_b32_e32 v20, 4, v20
	s_and_b32 s4, s20, 0x100
	s_and_b32 s5, s5, 0x600
	v_lshl_add_u64 v[18:19], v[18:19], 0, v[20:21]
	s_or_b32 s20, s5, s4
	v_cmp_gt_u32_e64 s[4:5], 32, v43
	v_lshl_add_u32 v212, v41, 2, v204
	v_lshl_add_u64 v[196:197], s[26:27], 0, v[18:19]
	v_mov_b64_e32 v[64:65], v[16:17]
	v_mov_b64_e32 v[48:49], v[16:17]
	v_mov_b64_e32 v[32:33], v[16:17]
	s_mov_b32 s21, s40
	s_mov_b32 s41, 0
	v_mov_b64_e32 v[62:63], v[14:15]
	v_mov_b64_e32 v[60:61], v[12:13]
	v_mov_b64_e32 v[58:59], v[10:11]
	v_mov_b64_e32 v[56:57], v[8:9]
	v_mov_b64_e32 v[54:55], v[6:7]
	v_mov_b64_e32 v[52:53], v[4:5]
	v_mov_b64_e32 v[50:51], v[2:3]
	v_mov_b64_e32 v[46:47], v[14:15]
	v_mov_b64_e32 v[44:45], v[12:13]
	v_mov_b64_e32 v[42:43], v[10:11]
	v_mov_b64_e32 v[40:41], v[8:9]
	v_mov_b64_e32 v[38:39], v[6:7]
	v_mov_b64_e32 v[36:37], v[4:5]
	v_mov_b64_e32 v[34:35], v[2:3]
	v_mov_b64_e32 v[30:31], v[14:15]
	v_mov_b64_e32 v[28:29], v[12:13]
	v_mov_b64_e32 v[26:27], v[10:11]
	v_mov_b64_e32 v[24:25], v[8:9]
	v_mov_b64_e32 v[22:23], v[6:7]
	v_mov_b64_e32 v[20:21], v[4:5]
	v_mov_b64_e32 v[18:19], v[2:3]
	s_mov_b32 s48, 0
	v_mov_b32_e32 v67, v66
	v_mov_b32_e32 v68, v66
	v_mov_b32_e32 v69, v66
	v_mov_b32_e32 v70, v66
	v_mov_b32_e32 v71, v66
	v_mov_b32_e32 v72, v66
	v_mov_b32_e32 v73, v66
	v_mov_b32_e32 v74, v66
	v_mov_b32_e32 v75, v66
	v_mov_b32_e32 v76, v66
	v_mov_b32_e32 v77, v66
	v_mov_b32_e32 v78, v66
	v_mov_b32_e32 v79, v66
	v_mov_b32_e32 v80, v66
	v_mov_b32_e32 v81, v66
	s_mov_b32 s99, 1
	s_lshl_b32 s98, s99, 13
	v_add_u32_e32 v252, s98, v208
	v_add_u32_e32 v253, s98, v209
	v_add_u32_e32 v254, s98, v210
	v_add_u32_e32 v255, s98, v211
	ds_read_b128 v[236:239], v252 offset:49152
	ds_read_b128 v[240:243], v253 offset:49152
	ds_read_b128 v[244:247], v254 offset:49152
	ds_read_b128 v[248:251], v255 offset:49152
	v_mov_b32_e32 v226, v213

; #define SBAR() __builtin_amdgcn_sched_barrier(0)
; __device__ __forceinline__ void qkt(f32x16& p0, f32x16& p1, const char* Ks, const bf16x8* qr, int r32, int hi, const f32x16& negm) {
;   bf16x8 ka[4], kb[4];
; #pragma unroll
;   for (int d0 = 0; d0 < 4; ++d0) { const int cb = (d0 * 16 + hi * 8) * 2;
;     ka[d0] = *reinterpret_cast<const bf16x8*>(Ks + KSWZ(r32, cb)); }
; #pragma unroll
;   for (int d0 = 0; d0 < 4; ++d0) { const int cb = (d0 * 16 + hi * 8) * 2;
;     kb[d0] = *reinterpret_cast<const bf16x8*>(Ks + KSWZ(32 + r32, cb)); }
;   asm volatile("s_waitcnt lgkmcnt(0)" ::: "memory");
; #pragma unroll
;   for (int d0 = 0; d0 < 4; ++d0) { asm volatile("" : "+v"(ka[d0])); asm volatile("" : "+v"(kb[d0])); }
;   SBAR();
;   p0 = __builtin_amdgcn_mfma_f32_32x32x16_bf16(ka[0], qr[0], negm, 0, 0, 0);
;   p0 = __builtin_amdgcn_mfma_f32_32x32x16_bf16(ka[1], qr[1], p0, 0, 0, 0);
;   p0 = __builtin_amdgcn_mfma_f32_32x32x16_bf16(ka[2], qr[2], p0, 0, 0, 0);
;   p0 = __builtin_amdgcn_mfma_f32_32x32x16_bf16(ka[3], qr[3], p0, 0, 0, 0);
;   p1 = __builtin_amdgcn_mfma_f32_32x32x16_bf16(kb[0], qr[0], negm, 0, 0, 0);
;   p1 = __builtin_amdgcn_mfma_f32_32x32x16_bf16(kb[1], qr[1], p1, 0, 0, 0);
;   p1 = __builtin_amdgcn_mfma_f32_32x32x16_bf16(kb[2], qr[2], p1, 0, 0, 0);
;   p1 = __builtin_amdgcn_mfma_f32_32x32x16_bf16(kb[3], qr[3], p1, 0, 0, 0);
;   SBAR();
; }
; __device__ __forceinline__ int v_st(int k, int c) { const int kk = (k & ~0xC) | ((k & 4) << 1) | ((k & 8) >> 1); return ((kk >> 3) * 4 + (c >> 5)) * 512 + ((kk & 7) * 32 + (c & 31)) * 2; }
; __device__ __forceinline__ int v_rd_base(int lane) { return ((lane & 3) << 3) | (((lane >> 2) & 3) << 6) | (((lane >> 4) & 1) << 5) | (((lane >> 5) & 1) << 8); }
; template <int OFF> __device__ __forceinline__ s16x4 tr_read(int vb) {
;   s16x4 r; asm volatile("ds_read_b64_tr_b16 %0, %1 offset:%2" : "=&v"(r) : "v"(vb), "i"(OFF) : "memory"); return r;
; }
; template <int D0> __device__ __forceinline__ void pv_rd(s16x4 (&v)[8], int vb) {
;   v[0] = tr_read<v_rd_off(D0, 0, 0)>(vb); v[1] = tr_read<v_rd_off(D0, 0, 1)>(vb); v[2] = tr_read<v_rd_off(D0, 1, 0)>(vb); v[3] = tr_read<v_rd_off(D0, 1, 1)>(vb);
;   v[4] = tr_read<v_rd_off(D0, 2, 0)>(vb); v[5] = tr_read<v_rd_off(D0, 2, 1)>(vb); v[6] = tr_read<v_rd_off(D0, 3, 0)>(vb); v[7] = tr_read<v_rd_off(D0, 3, 1)>(vb);
; }
.LBB0_333:
	s_lshl_b32 s49, s48, 14
	s_waitcnt lgkmcnt(0)
	v_mfma_f32_32x32x16_bf16 v[82:97], v[236:239], v[130:133], v[66:81]
	ds_read_b128 v[218:221], v252 offset:53248
	ds_read_b128 v[222:225], v253 offset:53248
	ds_read_b128 v[198:201], v254 offset:53248
	v_mfma_f32_32x32x16_bf16 v[82:97], v[240:243], v[134:137], v[82:97]
	ds_read_b128 v[214:217], v255 offset:53248
	ds_read_b64_tr_b16 v[98:99], v226 offset:0x0
	ds_read_b64_tr_b16 v[100:101], v226 offset:0x800
	v_mfma_f32_32x32x16_bf16 v[82:97], v[244:247], v[138:141], v[82:97]
	ds_read_b64_tr_b16 v[102:103], v226 offset:0x1000
	ds_read_b64_tr_b16 v[104:105], v226 offset:0x1800
	ds_read_b64_tr_b16 v[106:107], v226 offset:0x2000
	v_mfma_f32_32x32x16_bf16 v[82:97], v[248:251], v[142:145], v[82:97]
	ds_read_b64_tr_b16 v[108:109], v226 offset:0x2800
	ds_read_b64_tr_b16 v[110:111], v226 offset:0x3000
	ds_read_b64_tr_b16 v[112:113], v226 offset:0x3800
	s_waitcnt lgkmcnt(8)
	v_mfma_f32_32x32x16_bf16 v[114:129], v[218:221], v[130:133], v[66:81]
	ds_read_b64_tr_b16 v[218:219], v226 offset:0x2200
	ds_read_b64_tr_b16 v[220:221], v226 offset:0x2a00
	v_mfma_f32_32x32x16_bf16 v[114:129], v[222:225], v[134:137], v[114:129]
	ds_read_b64_tr_b16 v[222:223], v226 offset:0x3200
	ds_read_b64_tr_b16 v[224:225], v226 offset:0x3a00
	v_mfma_f32_32x32x16_bf16 v[114:129], v[198:201], v[138:141], v[114:129]
	ds_read_b64_tr_b16 v[198:199], v226 offset:0x200
	ds_read_b64_tr_b16 v[200:201], v226 offset:0xa00
	v_mfma_f32_32x32x16_bf16 v[114:129], v[214:217], v[142:145], v[114:129]
	ds_read_b64_tr_b16 v[214:215], v226 offset:0x1200
	ds_read_b64_tr_b16 v[216:217], v226 offset:0x1a00
	s_waitcnt lgkmcnt(8)
	v_mfma_f32_32x32x16_bf16 v[2:17], v[170:173], v[98:101], v[2:17]
	ds_read_b64_tr_b16 v[98:99], v226 offset:0x400
	ds_read_b64_tr_b16 v[100:101], v226 offset:0xc00
	v_mfma_f32_32x32x16_bf16 v[2:17], v[174:177], v[102:105], v[2:17]
	ds_read_b64_tr_b16 v[102:103], v226 offset:0x1400
	ds_read_b64_tr_b16 v[104:105], v226 offset:0x1c00
	v_mfma_f32_32x32x16_bf16 v[2:17], v[178:181], v[106:109], v[2:17]
	ds_read_b64_tr_b16 v[106:107], v226 offset:0x2400
	ds_read_b64_tr_b16 v[108:109], v226 offset:0x2c00
	v_mfma_f32_32x32x16_bf16 v[2:17], v[182:185], v[110:113], v[2:17]
	ds_read_b64_tr_b16 v[110:111], v226 offset:0x3400
	ds_read_b64_tr_b16 v[112:113], v226 offset:0x3c00
	s_lshl_b32 s98, s46, 14
	s_waitcnt vmcnt(3)
	v_add_u32_e32 v252, s98, v205
	v_lshl_add_u32 v254, s46, 13, v207
	v_add_u32_e32 v253, s98, v206
	s_waitcnt lgkmcnt(8)
	v_mfma_f32_32x32x16_bf16 v[50:65], v[170:173], v[198:201], v[50:65]
	ds_read_b64_tr_b16 v[198:199], v226 offset:0x600
	ds_read_b64_tr_b16 v[200:201], v226 offset:0xe00
	ds_write_b128 v252, v[146:149]
	v_mfma_f32_32x32x16_bf16 v[50:65], v[174:177], v[214:217], v[50:65]
	ds_read_b64_tr_b16 v[214:215], v226 offset:0x1600
	ds_read_b64_tr_b16 v[216:217], v226 offset:0x1e00
	ds_write_b128 v253, v[150:153]
	v_mfma_f32_32x32x16_bf16 v[50:65], v[178:181], v[218:221], v[50:65]
	ds_read_b64_tr_b16 v[218:219], v226 offset:0x2600
	ds_read_b64_tr_b16 v[220:221], v226 offset:0x2e00
	ds_write_b128 v254, v[158:161] offset:49152
	v_mfma_f32_32x32x16_bf16 v[50:65], v[182:185], v[222:225], v[50:65]
	ds_read_b64_tr_b16 v[222:223], v226 offset:0x3600
	ds_read_b64_tr_b16 v[224:225], v226 offset:0x3e00
	s_waitcnt lgkmcnt(11)
	v_mfma_f32_32x32x16_bf16 v[34:49], v[170:173], v[98:101], v[34:49]
	v_mfma_f32_32x32x16_bf16 v[34:49], v[174:177], v[102:105], v[34:49]
	v_mfma_f32_32x32x16_bf16 v[34:49], v[178:181], v[106:109], v[34:49]
	v_mfma_f32_32x32x16_bf16 v[34:49], v[182:185], v[110:113], v[34:49]
	s_waitcnt lgkmcnt(0)
	v_mfma_f32_32x32x16_bf16 v[18:33], v[170:173], v[198:201], v[18:33]
	v_mfma_f32_32x32x16_bf16 v[18:33], v[174:177], v[214:217], v[18:33]
	v_mfma_f32_32x32x16_bf16 v[18:33], v[178:181], v[218:221], v[18:33]
	v_mfma_f32_32x32x16_bf16 v[18:33], v[182:185], v[222:225], v[18:33]
	s_barrier
	s_cmp_gt_u32 s41, 63
	v_lshl_add_u64 v[200:201], v[194:195], 0, s[20:21]
	v_lshl_add_u64 v[198:199], v[196:197], 0, s[20:21]
	s_cbranch_scc1 .LBB0_335
	v_add_co_u32_e32 v98, vcc, 0x20cb8000, v200
	s_nop 1
	v_addc_co_u32_e32 v99, vcc, 0, v201, vcc
	v_add_co_u32_e32 v100, vcc, 0x20cc8000, v200
	s_nop 1
	v_addc_co_u32_e32 v101, vcc, 0, v201, vcc
	global_load_dwordx4 v[146:149], v[98:99], off offset:256
	global_load_dwordx4 v[150:153], v[100:101], off offset:256
	v_add_co_u32_e32 v98, vcc, 0x1c8b8000, v198
	s_nop 1
	v_addc_co_u32_e32 v99, vcc, 0, v199, vcc
	global_load_dwordx4 v[158:161], v[98:99], off offset:256

; #define SBAR() __builtin_amdgcn_sched_barrier(0)
; #define SLOAD(S, k0) do { vs##S##0 = *reinterpret_cast<const bf16x8*>(&Vh[(size_t)((k0) + sr) * LDK + sc]); \
;     vs##S##1 = *reinterpret_cast<const bf16x8*>(&Vh[(size_t)((k0) + 32 + sr) * LDK + sc]); \
;     ks##S = *reinterpret_cast<const bf16x8*>(&Kh[(size_t)((k0) + kr) * LDK + kc]); } while (0)
; #define SWRITE(b, S) do { *(bf16x8*)(V_lds + (b) * SHM_V + vst0) = vs##S##0; *(bf16x8*)(V_lds + (b) * SHM_V + vst1) = vs##S##1; \
;     *(bf16x8*)(K_lds + (b) * SHM_K + kst) = ks##S; } while (0)
; #define SWAIT() asm volatile("s_waitcnt vmcnt(3)" ::: "memory")
; #define SOFTMAX(FIRST) do { partialSM(p0, p1, m_reg, negm, al, FIRST); finishSM(p0, p1, al, l_reg, pa0, pa1, pa2, pa3); RESC(al); } while (0)
; __device__ __forceinline__ void pv_d0(f32x16* o, int vb, bf16x8 pa0, bf16x8 pa1, bf16x8 pa2, bf16x8 pa3) {
;   s16x4 va[8], vc[8];
;   pv_rd<0>(va, vb);
;   pv_rd<1>(vc, vb);
;   asm volatile("s_waitcnt lgkmcnt(8)" ::: "memory"); SBAR(); pv_mm(o[0], va, pa0, pa1, pa2, pa3); SBAR();
;   pv_rd<2>(va, vb); asm volatile("s_waitcnt lgkmcnt(8)" ::: "memory"); SBAR(); pv_mm(o[1], vc, pa0, pa1, pa2, pa3); SBAR();
;   pv_rd<3>(vc, vb); asm volatile("s_waitcnt lgkmcnt(8)" ::: "memory"); SBAR(); pv_mm(o[2], va, pa0, pa1, pa2, pa3); SBAR();
;   asm volatile("s_waitcnt lgkmcnt(0)" ::: "memory"); SBAR(); pv_mm(o[3], vc, pa0, pa1, pa2, pa3);
; }
; __device__ __forceinline__ void attn_stream(const u16* __restrict__ Qb, const u16* __restrict__ Kh, const u16* __restrict__ Vh,
;                                             int seq, char* lds, f32x16 (&o)[4]) {
;     ...
;     if (j + 4 < NT) SLOAD(A, (j + 4) * 64);
;     SOFTMAX(false);
;     SBAR(); __syncthreads(); SBAR();
;     if (j + 3 < NT) { SWAIT(); SWRITE(b0, B); }
;     if (j + 2 < NT) qkt(p0, p1, K_lds + b2 * SHM_K, qr, r32, hi, negm);
;     pv_d0(o, vb0 + b1 * SHM_V, pa0, pa1, pa2, pa3);
;     SBAR(); __syncthreads(); SBAR();
;     if (j + 5 < NT) SLOAD(B, (j + 5) * 64);
;     if (j + 2 < NT) SOFTMAX(false);
;     SBAR(); __syncthreads(); SBAR();
.LBB0_341:
	s_lshl_b32 s98, s46, 13
	v_add_u32_e32 v252, s98, v208
	v_add_u32_e32 v253, s98, v209
	v_add_u32_e32 v254, s98, v210
	v_add_u32_e32 v255, s98, v211
	ds_read_b128 v[236:239], v252 offset:49152
	ds_read_b128 v[240:243], v253 offset:49152
	ds_read_b128 v[244:247], v254 offset:49152
	ds_read_b128 v[248:251], v255 offset:49152
	v_lshl_add_u32 v217, s47, 14, v213
	s_barrier
.LBB0_343:
	s_andn2_b64 s[6:7], exec, s[44:45]
	s_andn2_b64 vcc, exec, s[44:45]
	s_cbranch_vccnz .LBB0_345
	s_waitcnt lgkmcnt(0)
	v_mfma_f32_32x32x16_bf16 v[82:97], v[236:239], v[130:133], v[66:81]
	ds_read_b128 v[218:221], v252 offset:53248
	ds_read_b128 v[222:225], v253 offset:53248
	ds_read_b128 v[226:229], v254 offset:53248
	v_mfma_f32_32x32x16_bf16 v[82:97], v[240:243], v[134:137], v[82:97]
	ds_read_b128 v[230:233], v255 offset:53248
	ds_read_b64_tr_b16 v[98:99], v217 offset:0x0
	ds_read_b64_tr_b16 v[100:101], v217 offset:0x800
	v_mfma_f32_32x32x16_bf16 v[82:97], v[244:247], v[138:141], v[82:97]
	ds_read_b64_tr_b16 v[102:103], v217 offset:0x1000
	ds_read_b64_tr_b16 v[104:105], v217 offset:0x1800
	ds_read_b64_tr_b16 v[106:107], v217 offset:0x2000
	v_mfma_f32_32x32x16_bf16 v[82:97], v[248:251], v[142:145], v[82:97]
	ds_read_b64_tr_b16 v[108:109], v217 offset:0x2800
	ds_read_b64_tr_b16 v[110:111], v217 offset:0x3000
	ds_read_b64_tr_b16 v[112:113], v217 offset:0x3800
	s_waitcnt lgkmcnt(8)
	v_mfma_f32_32x32x16_bf16 v[114:129], v[218:221], v[130:133], v[66:81]
	ds_read_b64_tr_b16 v[218:219], v217 offset:0x200
	ds_read_b64_tr_b16 v[220:221], v217 offset:0xa00
	v_mfma_f32_32x32x16_bf16 v[114:129], v[222:225], v[134:137], v[114:129]
	ds_read_b64_tr_b16 v[222:223], v217 offset:0x1200
	ds_read_b64_tr_b16 v[224:225], v217 offset:0x1a00
	v_mfma_f32_32x32x16_bf16 v[114:129], v[226:229], v[138:141], v[114:129]
	ds_read_b64_tr_b16 v[226:227], v217 offset:0x2200
	ds_read_b64_tr_b16 v[228:229], v217 offset:0x2a00
	v_mfma_f32_32x32x16_bf16 v[114:129], v[230:233], v[142:145], v[114:129]
	ds_read_b64_tr_b16 v[230:231], v217 offset:0x3200
	ds_read_b64_tr_b16 v[232:233], v217 offset:0x3a00
	s_branch .Lattn_pvb2_1
.LBB0_345:
	ds_read_b64_tr_b16 v[98:99], v217 offset:0x0
	ds_read_b64_tr_b16 v[100:101], v217 offset:0x800
	ds_read_b64_tr_b16 v[102:103], v217 offset:0x1000
	ds_read_b64_tr_b16 v[104:105], v217 offset:0x1800
	ds_read_b64_tr_b16 v[106:107], v217 offset:0x2000
	ds_read_b64_tr_b16 v[108:109], v217 offset:0x2800
	ds_read_b64_tr_b16 v[110:111], v217 offset:0x3000
	ds_read_b64_tr_b16 v[112:113], v217 offset:0x3800
	ds_read_b64_tr_b16 v[218:219], v217 offset:0x200
	ds_read_b64_tr_b16 v[220:221], v217 offset:0xa00
	ds_read_b64_tr_b16 v[222:223], v217 offset:0x1200
	ds_read_b64_tr_b16 v[224:225], v217 offset:0x1a00
	ds_read_b64_tr_b16 v[226:227], v217 offset:0x2200
	ds_read_b64_tr_b16 v[228:229], v217 offset:0x2a00
	ds_read_b64_tr_b16 v[230:231], v217 offset:0x3200
	ds_read_b64_tr_b16 v[232:233], v217 offset:0x3a00
.Lattn_pvb2_1:
	s_waitcnt lgkmcnt(8)
	v_mfma_f32_32x32x16_bf16 v[2:17], v[170:173], v[98:101], v[2:17]
	ds_read_b64_tr_b16 v[98:99], v217 offset:0x400
	ds_read_b64_tr_b16 v[100:101], v217 offset:0xc00
	v_mfma_f32_32x32x16_bf16 v[2:17], v[174:177], v[102:105], v[2:17]
	ds_read_b64_tr_b16 v[102:103], v217 offset:0x1400
	ds_read_b64_tr_b16 v[104:105], v217 offset:0x1c00
	v_mfma_f32_32x32x16_bf16 v[2:17], v[178:181], v[106:109], v[2:17]
	ds_read_b64_tr_b16 v[106:107], v217 offset:0x2400
	ds_read_b64_tr_b16 v[108:109], v217 offset:0x2c00
	v_mfma_f32_32x32x16_bf16 v[2:17], v[182:185], v[110:113], v[2:17]
	ds_read_b64_tr_b16 v[110:111], v217 offset:0x3400
	ds_read_b64_tr_b16 v[112:113], v217 offset:0x3c00
	s_waitcnt vmcnt(3)
	s_cmp_lt_u32 s41, 64
	s_cbranch_scc1 .Lattn_oddw_1
	s_waitcnt vmcnt(0)
.Lattn_oddw_1:
	s_add_i32 s98, s49, 0
	v_add_u32_e32 v252, s98, v205
	v_lshl_add_u32 v254, s48, 13, v207
	v_add_u32_e32 v253, s98, v206
	s_waitcnt lgkmcnt(8)
	v_mfma_f32_32x32x16_bf16 v[50:65], v[170:173], v[218:221], v[50:65]
	ds_read_b64_tr_b16 v[218:219], v217 offset:0x600
	ds_read_b64_tr_b16 v[220:221], v217 offset:0xe00
	ds_write_b128 v252, v[154:157]
	v_mfma_f32_32x32x16_bf16 v[50:65], v[174:177], v[222:225], v[50:65]
	ds_read_b64_tr_b16 v[222:223], v217 offset:0x1600
	ds_read_b64_tr_b16 v[224:225], v217 offset:0x1e00
	ds_write_b128 v253, v[162:165]
	v_mfma_f32_32x32x16_bf16 v[50:65], v[178:181], v[226:229], v[50:65]
	ds_read_b64_tr_b16 v[226:227], v217 offset:0x2600
	ds_read_b64_tr_b16 v[228:229], v217 offset:0x2e00
	ds_write_b128 v254, v[166:169] offset:49152
	v_mfma_f32_32x32x16_bf16 v[50:65], v[182:185], v[230:233], v[50:65]
	ds_read_b64_tr_b16 v[230:231], v217 offset:0x3600
	ds_read_b64_tr_b16 v[232:233], v217 offset:0x3e00
	s_waitcnt lgkmcnt(11)
	v_mfma_f32_32x32x16_bf16 v[34:49], v[170:173], v[98:101], v[34:49]
	v_mfma_f32_32x32x16_bf16 v[34:49], v[174:177], v[102:105], v[34:49]
	v_mfma_f32_32x32x16_bf16 v[34:49], v[178:181], v[106:109], v[34:49]
	v_mfma_f32_32x32x16_bf16 v[34:49], v[182:185], v[110:113], v[34:49]
	s_waitcnt lgkmcnt(0)
	v_mfma_f32_32x32x16_bf16 v[18:33], v[170:173], v[218:221], v[18:33]
	v_mfma_f32_32x32x16_bf16 v[18:33], v[174:177], v[222:225], v[18:33]
	v_mfma_f32_32x32x16_bf16 v[18:33], v[178:181], v[226:229], v[18:33]
	v_mfma_f32_32x32x16_bf16 v[18:33], v[182:185], v[230:233], v[18:33]
	s_waitcnt lgkmcnt(0)
	s_barrier
	s_cmp_gt_u32 s41, 62
	s_cbranch_scc1 .LBB0_347
	v_add_co_u32_e32 v98, vcc, 0x20cd8000, v200
	s_nop 1
	v_addc_co_u32_e32 v99, vcc, 0, v201, vcc
	v_add_co_u32_e32 v100, vcc, 0x20ce8000, v200
	s_nop 1
	v_addc_co_u32_e32 v101, vcc, 0, v201, vcc
	global_load_dwordx4 v[154:157], v[98:99], off offset:256
	global_load_dwordx4 v[162:165], v[100:101], off offset:256
	v_add_co_u32_e32 v98, vcc, 0x1c8d8000, v198
	s_nop 1
	v_addc_co_u32_e32 v99, vcc, 0, v199, vcc
	global_load_dwordx4 v[166:169], v[98:99], off offset:256

; #define SBAR() __builtin_amdgcn_sched_barrier(0)
; __device__ __forceinline__ void attn_stream(const u16* __restrict__ Qb, const u16* __restrict__ Kh, const u16* __restrict__ Vh,
;                                             int seq, char* lds, f32x16 (&o)[4]) {
;     ...
;     SBAR(); __syncthreads(); SBAR();
;     t3 = b2;
.LBB0_355:
	s_add_i32 s41, s41, 2
	s_lshl_b32 s98, s48, 13
	v_add_u32_e32 v252, s98, v208
	v_add_u32_e32 v253, s98, v209
	v_add_u32_e32 v254, s98, v210
	v_add_u32_e32 v255, s98, v211
	ds_read_b128 v[236:239], v252 offset:49152
	ds_read_b128 v[240:243], v253 offset:49152
	ds_read_b128 v[244:247], v254 offset:49152
	ds_read_b128 v[248:251], v255 offset:49152
	v_lshl_add_u32 v226, s46, 14, v213
	s_barrier
	v_lshl_add_u64 v[194:195], v[194:195], 0, s[12:13]
	v_lshl_add_u64 v[196:197], v[196:197], 0, s[12:13]
	s_and_b64 vcc, exec, s[42:43]
	s_cbranch_vccnz .LBB0_359
	s_mov_b32 s48, s46
	s_branch .LBB0_331

; #define SBAR() __builtin_amdgcn_sched_barrier(0)
; __device__ __forceinline__ int opq(int x) { asm volatile("" : "+v"(x)); return x; }
; __device__ __forceinline__ int v_st(int k, int c) { const int kk = (k & ~0xC) | ((k & 4) << 1) | ((k & 8) >> 1); return ((kk >> 3) * 4 + (c >> 5)) * 512 + ((kk & 7) * 32 + (c & 31)) * 2; }
; __device__ __forceinline__ int v_rd_base(int lane) { return ((lane & 3) << 3) | (((lane >> 2) & 3) << 6) | (((lane >> 4) & 1) << 5) | (((lane >> 5) & 1) << 8); }
; #define SLOAD(S, k0) do { vs##S##0 = *reinterpret_cast<const bf16x8*>(&Vh[(size_t)((k0) + sr) * LDK + sc]); \
;     vs##S##1 = *reinterpret_cast<const bf16x8*>(&Vh[(size_t)((k0) + 32 + sr) * LDK + sc]); \
;     ks##S = *reinterpret_cast<const bf16x8*>(&Kh[(size_t)((k0) + kr) * LDK + kc]); } while (0)
; __device__ __forceinline__ void attn_stream(const u16* __restrict__ Qb, const u16* __restrict__ Kh, const u16* __restrict__ Vh,
;                                             int seq, char* lds, f32x16 (&o)[4]) {
;     ...
;   const int tid = opq((int)threadIdx.x), wid = tid >> 6, lane = tid & 63, r32 = lane & 31, hi = lane >> 5;
;   char* V_lds = lds; char* K_lds = lds + 3 * SHM_V;
;   float* wsl = (float*)(lds + 3 * SHM_V + 3 * SHM_K) + wid * 64; float* li_l = wsl; float* al_l = wsl + 32;
;   float m_reg = 0.f, l_reg = 0.f; bf16x8 qr[4]; f32x16 negm = {};
; #pragma unroll
;   for (int d = 0; d < 4; ++d) o[d] = f32x16{};
;   const u16* Qw = Qb + (size_t)(wid * 32 + r32) * LDQ + hi * 8;
; #pragma unroll
;   for (int d0 = 0; d0 < 4; ++d0) qr[d0] = *reinterpret_cast<const bf16x8*>(Qw + d0 * 16);
;   const int sr = tid >> 4, sc = (tid & 15) * 8, vst0 = v_st(sr, sc), vst1 = v_st(32 + sr, sc);
;   const int kr = tid >> 3, kc = (tid & 7) * 8, kst = KSWZ(kr, kc * 2);
;   const int vb0 = (int)(uintptr_t)(__attribute__((address_space(3))) char*)V_lds + v_rd_base(lane);
;   bf16x8 vsA0, vsA1, ksA, vsB0, vsB1, ksB;
;     ...
;   f32x16 p0, p1; float al; bf16x8 pa0, pa1, pa2, pa3; const int NT = seq / 64;
;     ...
;   const bool late = wid >= 4;
;   __syncthreads();
;   SLOAD(A, 0); SLOAD(B, 64); asm volatile("s_waitcnt vmcnt(0)" ::: "memory"); SWRITE(0, A); SWRITE(1, B);
;   SLOAD(A, 128); SLOAD(B, 192);
;   __syncthreads();
;   qkt(p0, p1, K_lds, qr, r32, hi, negm); SOFTMAX(true); SBAR();
;   if (late) __syncthreads();
;   int t3 = 0;
.LBB0_370:
	s_or_b64 exec, exec, s[4:5]
	v_lshlrev_b32_e32 v19, 4, v43
	v_lshlrev_b32_e32 v18, 3, v43
	v_and_b32_e32 v19, 0xc0, v19
	v_lshlrev_b32_e32 v20, 1, v43
	v_and_or_b32 v19, v18, 24, v19
	v_and_b32_e32 v20, 32, v20
	v_and_b32_e32 v18, 0x100, v18
	v_or3_b32 v18, v19, v20, v18
	v_and_b32_e32 v20, 15, v40
	v_add_u32_e32 v213, 0, v18
	v_lshl_add_u64 v[18:19], s[56:57], 0, v[34:35]
	v_lshlrev_b32_e32 v20, 4, v20
	v_mov_b32_e32 v21, v191
	v_lshl_add_u64 v[18:19], v[18:19], 0, v[20:21]
	v_and_b32_e32 v20, 7, v40
	v_lshl_add_u64 v[194:195], s[26:27], 0, v[18:19]
	v_lshl_add_u64 v[18:19], s[56:57], 0, v[36:37]
	v_lshlrev_b32_e32 v20, 4, v20
	v_lshl_add_u64 v[18:19], v[18:19], 0, v[20:21]
	v_cmp_gt_u32_e64 s[4:5], 32, v43
	v_lshl_add_u32 v212, v41, 2, v204
	v_lshl_add_u64 v[196:197], s[26:27], 0, v[18:19]
	v_mov_b64_e32 v[64:65], v[16:17]
	v_mov_b64_e32 v[48:49], v[16:17]
	v_mov_b64_e32 v[32:33], v[16:17]
	s_mov_b32 s38, 0
	v_mov_b64_e32 v[62:63], v[14:15]
	v_mov_b64_e32 v[60:61], v[12:13]
	v_mov_b64_e32 v[58:59], v[10:11]
	v_mov_b64_e32 v[56:57], v[8:9]
	v_mov_b64_e32 v[54:55], v[6:7]
	v_mov_b64_e32 v[52:53], v[4:5]
	v_mov_b64_e32 v[50:51], v[2:3]
	v_mov_b64_e32 v[46:47], v[14:15]
	v_mov_b64_e32 v[44:45], v[12:13]
	v_mov_b64_e32 v[42:43], v[10:11]
	v_mov_b64_e32 v[40:41], v[8:9]
	v_mov_b64_e32 v[38:39], v[6:7]
	v_mov_b64_e32 v[36:37], v[4:5]
	v_mov_b64_e32 v[34:35], v[2:3]
	v_mov_b64_e32 v[30:31], v[14:15]
	v_mov_b64_e32 v[28:29], v[12:13]
	v_mov_b64_e32 v[26:27], v[10:11]
	v_mov_b64_e32 v[24:25], v[8:9]
	v_mov_b64_e32 v[22:23], v[6:7]
	v_mov_b64_e32 v[20:21], v[4:5]
	v_mov_b64_e32 v[18:19], v[2:3]
	s_mov_b32 s42, 0
	v_mov_b32_e32 v67, v66
	v_mov_b32_e32 v68, v66
	v_mov_b32_e32 v69, v66
	v_mov_b32_e32 v70, v66
	v_mov_b32_e32 v71, v66
	v_mov_b32_e32 v72, v66
	v_mov_b32_e32 v73, v66
	v_mov_b32_e32 v74, v66
	v_mov_b32_e32 v75, v66
	v_mov_b32_e32 v76, v66
	v_mov_b32_e32 v77, v66
	v_mov_b32_e32 v78, v66
	v_mov_b32_e32 v79, v66
	v_mov_b32_e32 v80, v66
	v_mov_b32_e32 v81, v66
	s_mov_b32 s99, 1
	s_lshl_b32 s98, s99, 13
	v_add_u32_e32 v252, s98, v208
	v_add_u32_e32 v253, s98, v209
	v_add_u32_e32 v254, s98, v210
	v_add_u32_e32 v255, s98, v211
	ds_read_b128 v[236:239], v252 offset:49152
	ds_read_b128 v[240:243], v253 offset:49152
	ds_read_b128 v[244:247], v254 offset:49152
	ds_read_b128 v[248:251], v255 offset:49152
	v_mov_b32_e32 v226, v213

; #define SBAR() __builtin_amdgcn_sched_barrier(0)
; __device__ __forceinline__ void qkt(f32x16& p0, f32x16& p1, const char* Ks, const bf16x8* qr, int r32, int hi, const f32x16& negm) {
;   bf16x8 ka[4], kb[4];
; #pragma unroll
;   for (int d0 = 0; d0 < 4; ++d0) { const int cb = (d0 * 16 + hi * 8) * 2;
;     ka[d0] = *reinterpret_cast<const bf16x8*>(Ks + KSWZ(r32, cb)); }
; #pragma unroll
;   for (int d0 = 0; d0 < 4; ++d0) { const int cb = (d0 * 16 + hi * 8) * 2;
;     kb[d0] = *reinterpret_cast<const bf16x8*>(Ks + KSWZ(32 + r32, cb)); }
;   asm volatile("s_waitcnt lgkmcnt(0)" ::: "memory");
; #pragma unroll
;   for (int d0 = 0; d0 < 4; ++d0) { asm volatile("" : "+v"(ka[d0])); asm volatile("" : "+v"(kb[d0])); }
;   SBAR();
;   p0 = __builtin_amdgcn_mfma_f32_32x32x16_bf16(ka[0], qr[0], negm, 0, 0, 0);
;   p0 = __builtin_amdgcn_mfma_f32_32x32x16_bf16(ka[1], qr[1], p0, 0, 0, 0);
;   p0 = __builtin_amdgcn_mfma_f32_32x32x16_bf16(ka[2], qr[2], p0, 0, 0, 0);
;   p0 = __builtin_amdgcn_mfma_f32_32x32x16_bf16(ka[3], qr[3], p0, 0, 0, 0);
;   p1 = __builtin_amdgcn_mfma_f32_32x32x16_bf16(kb[0], qr[0], negm, 0, 0, 0);
;   p1 = __builtin_amdgcn_mfma_f32_32x32x16_bf16(kb[1], qr[1], p1, 0, 0, 0);
;   p1 = __builtin_amdgcn_mfma_f32_32x32x16_bf16(kb[2], qr[2], p1, 0, 0, 0);
;   p1 = __builtin_amdgcn_mfma_f32_32x32x16_bf16(kb[3], qr[3], p1, 0, 0, 0);
;   SBAR();
; }
; __device__ __forceinline__ int v_st(int k, int c) { const int kk = (k & ~0xC) | ((k & 4) << 1) | ((k & 8) >> 1); return ((kk >> 3) * 4 + (c >> 5)) * 512 + ((kk & 7) * 32 + (c & 31)) * 2; }
; __device__ __forceinline__ int v_rd_base(int lane) { return ((lane & 3) << 3) | (((lane >> 2) & 3) << 6) | (((lane >> 4) & 1) << 5) | (((lane >> 5) & 1) << 8); }
; template <int OFF> __device__ __forceinline__ s16x4 tr_read(int vb) {
;   s16x4 r; asm volatile("ds_read_b64_tr_b16 %0, %1 offset:%2" : "=&v"(r) : "v"(vb), "i"(OFF) : "memory"); return r;
; }
; template <int D0> __device__ __forceinline__ void pv_rd(s16x4 (&v)[8], int vb) {
;   v[0] = tr_read<v_rd_off(D0, 0, 0)>(vb); v[1] = tr_read<v_rd_off(D0, 0, 1)>(vb); v[2] = tr_read<v_rd_off(D0, 1, 0)>(vb); v[3] = tr_read<v_rd_off(D0, 1, 1)>(vb);
;   v[4] = tr_read<v_rd_off(D0, 2, 0)>(vb); v[5] = tr_read<v_rd_off(D0, 2, 1)>(vb); v[6] = tr_read<v_rd_off(D0, 3, 0)>(vb); v[7] = tr_read<v_rd_off(D0, 3, 1)>(vb);
; }
.LBB0_373:
	s_lshl_b32 s43, s42, 14
	s_waitcnt lgkmcnt(0)
	v_mfma_f32_32x32x16_bf16 v[82:97], v[236:239], v[130:133], v[66:81]
	ds_read_b128 v[218:221], v252 offset:53248
	ds_read_b128 v[222:225], v253 offset:53248
	ds_read_b128 v[198:201], v254 offset:53248
	v_mfma_f32_32x32x16_bf16 v[82:97], v[240:243], v[134:137], v[82:97]
	ds_read_b128 v[214:217], v255 offset:53248
	ds_read_b64_tr_b16 v[98:99], v226 offset:0x0
	ds_read_b64_tr_b16 v[100:101], v226 offset:0x800
	v_mfma_f32_32x32x16_bf16 v[82:97], v[244:247], v[138:141], v[82:97]
	ds_read_b64_tr_b16 v[102:103], v226 offset:0x1000
	ds_read_b64_tr_b16 v[104:105], v226 offset:0x1800
	ds_read_b64_tr_b16 v[106:107], v226 offset:0x2000
	v_mfma_f32_32x32x16_bf16 v[82:97], v[248:251], v[142:145], v[82:97]
	ds_read_b64_tr_b16 v[108:109], v226 offset:0x2800
	ds_read_b64_tr_b16 v[110:111], v226 offset:0x3000
	ds_read_b64_tr_b16 v[112:113], v226 offset:0x3800
	s_waitcnt lgkmcnt(8)
	v_mfma_f32_32x32x16_bf16 v[114:129], v[218:221], v[130:133], v[66:81]
	ds_read_b64_tr_b16 v[218:219], v226 offset:0x2200
	ds_read_b64_tr_b16 v[220:221], v226 offset:0x2a00
	v_mfma_f32_32x32x16_bf16 v[114:129], v[222:225], v[134:137], v[114:129]
	ds_read_b64_tr_b16 v[222:223], v226 offset:0x3200
	ds_read_b64_tr_b16 v[224:225], v226 offset:0x3a00
	v_mfma_f32_32x32x16_bf16 v[114:129], v[198:201], v[138:141], v[114:129]
	ds_read_b64_tr_b16 v[198:199], v226 offset:0x200
	ds_read_b64_tr_b16 v[200:201], v226 offset:0xa00
	v_mfma_f32_32x32x16_bf16 v[114:129], v[214:217], v[142:145], v[114:129]
	ds_read_b64_tr_b16 v[214:215], v226 offset:0x1200
	ds_read_b64_tr_b16 v[216:217], v226 offset:0x1a00
	s_waitcnt lgkmcnt(8)
	v_mfma_f32_32x32x16_bf16 v[2:17], v[170:173], v[98:101], v[2:17]
	ds_read_b64_tr_b16 v[98:99], v226 offset:0x400
	ds_read_b64_tr_b16 v[100:101], v226 offset:0xc00
	v_mfma_f32_32x32x16_bf16 v[2:17], v[174:177], v[102:105], v[2:17]
	ds_read_b64_tr_b16 v[102:103], v226 offset:0x1400
	ds_read_b64_tr_b16 v[104:105], v226 offset:0x1c00
	v_mfma_f32_32x32x16_bf16 v[2:17], v[178:181], v[106:109], v[2:17]
	ds_read_b64_tr_b16 v[106:107], v226 offset:0x2400
	ds_read_b64_tr_b16 v[108:109], v226 offset:0x2c00
	v_mfma_f32_32x32x16_bf16 v[2:17], v[182:185], v[110:113], v[2:17]
	ds_read_b64_tr_b16 v[110:111], v226 offset:0x3400
	ds_read_b64_tr_b16 v[112:113], v226 offset:0x3c00
	s_lshl_b32 s98, s39, 14
	s_waitcnt vmcnt(3)
	v_add_u32_e32 v252, s98, v205
	v_lshl_add_u32 v254, s39, 13, v207
	v_add_u32_e32 v253, s98, v206
	s_waitcnt lgkmcnt(8)
	v_mfma_f32_32x32x16_bf16 v[50:65], v[170:173], v[198:201], v[50:65]
	ds_read_b64_tr_b16 v[198:199], v226 offset:0x600
	ds_read_b64_tr_b16 v[200:201], v226 offset:0xe00
	ds_write_b128 v252, v[146:149]
	v_mfma_f32_32x32x16_bf16 v[50:65], v[174:177], v[214:217], v[50:65]
	ds_read_b64_tr_b16 v[214:215], v226 offset:0x1600
	ds_read_b64_tr_b16 v[216:217], v226 offset:0x1e00
	ds_write_b128 v253, v[150:153]
	v_mfma_f32_32x32x16_bf16 v[50:65], v[178:181], v[218:221], v[50:65]
	ds_read_b64_tr_b16 v[218:219], v226 offset:0x2600
	ds_read_b64_tr_b16 v[220:221], v226 offset:0x2e00
	ds_write_b128 v254, v[158:161] offset:49152
	v_mfma_f32_32x32x16_bf16 v[50:65], v[182:185], v[222:225], v[50:65]
	ds_read_b64_tr_b16 v[222:223], v226 offset:0x3600
	ds_read_b64_tr_b16 v[224:225], v226 offset:0x3e00
	s_waitcnt lgkmcnt(11)
	v_mfma_f32_32x32x16_bf16 v[34:49], v[170:173], v[98:101], v[34:49]
	v_mfma_f32_32x32x16_bf16 v[34:49], v[174:177], v[102:105], v[34:49]
	v_mfma_f32_32x32x16_bf16 v[34:49], v[178:181], v[106:109], v[34:49]
	v_mfma_f32_32x32x16_bf16 v[34:49], v[182:185], v[110:113], v[34:49]
	s_waitcnt lgkmcnt(0)
	v_mfma_f32_32x32x16_bf16 v[18:33], v[170:173], v[198:201], v[18:33]
	v_mfma_f32_32x32x16_bf16 v[18:33], v[174:177], v[214:217], v[18:33]
	v_mfma_f32_32x32x16_bf16 v[18:33], v[178:181], v[218:221], v[18:33]
	v_mfma_f32_32x32x16_bf16 v[18:33], v[182:185], v[222:225], v[18:33]
	s_barrier
	s_cmp_gt_u32 s38, 63
	v_lshl_add_u64 v[200:201], v[194:195], 0, s[20:21]
	v_lshl_add_u64 v[198:199], v[196:197], 0, s[20:21]
	s_cbranch_scc1 .LBB0_375
	v_add_co_u32_e32 v98, vcc, 0x20cb8000, v200
	s_nop 1
	v_addc_co_u32_e32 v99, vcc, 0, v201, vcc
	v_add_co_u32_e32 v100, vcc, 0x20cc8000, v200
	s_nop 1
	v_addc_co_u32_e32 v101, vcc, 0, v201, vcc
	global_load_dwordx4 v[146:149], v[98:99], off offset:256
	global_load_dwordx4 v[150:153], v[100:101], off offset:256
	v_add_co_u32_e32 v98, vcc, 0x1c8b8000, v198
	s_nop 1
	v_addc_co_u32_e32 v99, vcc, 0, v199, vcc
	global_load_dwordx4 v[158:161], v[98:99], off offset:384

; #define SBAR() __builtin_amdgcn_sched_barrier(0)
; #define SLOAD(S, k0) do { vs##S##0 = *reinterpret_cast<const bf16x8*>(&Vh[(size_t)((k0) + sr) * LDK + sc]); \
;     vs##S##1 = *reinterpret_cast<const bf16x8*>(&Vh[(size_t)((k0) + 32 + sr) * LDK + sc]); \
;     ks##S = *reinterpret_cast<const bf16x8*>(&Kh[(size_t)((k0) + kr) * LDK + kc]); } while (0)
; #define SWRITE(b, S) do { *(bf16x8*)(V_lds + (b) * SHM_V + vst0) = vs##S##0; *(bf16x8*)(V_lds + (b) * SHM_V + vst1) = vs##S##1; \
;     *(bf16x8*)(K_lds + (b) * SHM_K + kst) = ks##S; } while (0)
; __device__ __forceinline__ void qkt(f32x16& p0, f32x16& p1, const char* Ks, const bf16x8* qr, int r32, int hi, const f32x16& negm) {
;   bf16x8 ka[4], kb[4];
; #pragma unroll
;   for (int d0 = 0; d0 < 4; ++d0) { const int cb = (d0 * 16 + hi * 8) * 2;
;     ka[d0] = *reinterpret_cast<const bf16x8*>(Ks + KSWZ(r32, cb)); }
; #pragma unroll
;   for (int d0 = 0; d0 < 4; ++d0) { const int cb = (d0 * 16 + hi * 8) * 2;
;     kb[d0] = *reinterpret_cast<const bf16x8*>(Ks + KSWZ(32 + r32, cb)); }
;   asm volatile("s_waitcnt lgkmcnt(0)" ::: "memory");
; #pragma unroll
;   for (int d0 = 0; d0 < 4; ++d0) { asm volatile("" : "+v"(ka[d0])); asm volatile("" : "+v"(kb[d0])); }
;   SBAR();
;   p0 = __builtin_amdgcn_mfma_f32_32x32x16_bf16(ka[0], qr[0], negm, 0, 0, 0);
;   p0 = __builtin_amdgcn_mfma_f32_32x32x16_bf16(ka[1], qr[1], p0, 0, 0, 0);
;   p0 = __builtin_amdgcn_mfma_f32_32x32x16_bf16(ka[2], qr[2], p0, 0, 0, 0);
;   p0 = __builtin_amdgcn_mfma_f32_32x32x16_bf16(ka[3], qr[3], p0, 0, 0, 0);
;   p1 = __builtin_amdgcn_mfma_f32_32x32x16_bf16(kb[0], qr[0], negm, 0, 0, 0);
;   p1 = __builtin_amdgcn_mfma_f32_32x32x16_bf16(kb[1], qr[1], p1, 0, 0, 0);
;   p1 = __builtin_amdgcn_mfma_f32_32x32x16_bf16(kb[2], qr[2], p1, 0, 0, 0);
;   p1 = __builtin_amdgcn_mfma_f32_32x32x16_bf16(kb[3], qr[3], p1, 0, 0, 0);
; __device__ __forceinline__ void attn_stream(const u16* __restrict__ Qb, const u16* __restrict__ Kh, const u16* __restrict__ Vh,
;                                             int seq, char* lds, f32x16 (&o)[4]) {
;     ...
;     if (j + 4 < NT) SLOAD(A, (j + 4) * 64);
;     SOFTMAX(false);
;     SBAR(); __syncthreads(); SBAR();
;     if (j + 3 < NT) { SWAIT(); SWRITE(b0, B); }
;     if (j + 2 < NT) qkt(p0, p1, K_lds + b2 * SHM_K, qr, r32, hi, negm);
;     pv_d0(o, vb0 + b1 * SHM_V, pa0, pa1, pa2, pa3);
.LBB0_381:
	s_lshl_b32 s98, s39, 13
	v_add_u32_e32 v252, s98, v208
	v_add_u32_e32 v253, s98, v209
	v_add_u32_e32 v254, s98, v210
	v_add_u32_e32 v255, s98, v211
	ds_read_b128 v[236:239], v252 offset:49152
	ds_read_b128 v[240:243], v253 offset:49152
	ds_read_b128 v[244:247], v254 offset:49152
	ds_read_b128 v[248:251], v255 offset:49152
	v_lshl_add_u32 v217, s41, 14, v213
	s_barrier
.LBB0_383:
	s_andn2_b64 s[6:7], exec, s[34:35]
	s_andn2_b64 vcc, exec, s[34:35]
	s_cbranch_vccnz .LBB0_385
	s_waitcnt lgkmcnt(0)
	v_mfma_f32_32x32x16_bf16 v[82:97], v[236:239], v[130:133], v[66:81]
	ds_read_b128 v[218:221], v252 offset:53248
	ds_read_b128 v[222:225], v253 offset:53248
	ds_read_b128 v[226:229], v254 offset:53248
	v_mfma_f32_32x32x16_bf16 v[82:97], v[240:243], v[134:137], v[82:97]
	ds_read_b128 v[230:233], v255 offset:53248
	ds_read_b64_tr_b16 v[98:99], v217 offset:0x0
	ds_read_b64_tr_b16 v[100:101], v217 offset:0x800
	v_mfma_f32_32x32x16_bf16 v[82:97], v[244:247], v[138:141], v[82:97]
	ds_read_b64_tr_b16 v[102:103], v217 offset:0x1000
	ds_read_b64_tr_b16 v[104:105], v217 offset:0x1800
	ds_read_b64_tr_b16 v[106:107], v217 offset:0x2000
	v_mfma_f32_32x32x16_bf16 v[82:97], v[248:251], v[142:145], v[82:97]
	ds_read_b64_tr_b16 v[108:109], v217 offset:0x2800
	ds_read_b64_tr_b16 v[110:111], v217 offset:0x3000
	ds_read_b64_tr_b16 v[112:113], v217 offset:0x3800
	s_waitcnt lgkmcnt(8)
	v_mfma_f32_32x32x16_bf16 v[114:129], v[218:221], v[130:133], v[66:81]
	ds_read_b64_tr_b16 v[218:219], v217 offset:0x200
	ds_read_b64_tr_b16 v[220:221], v217 offset:0xa00
	v_mfma_f32_32x32x16_bf16 v[114:129], v[222:225], v[134:137], v[114:129]
	ds_read_b64_tr_b16 v[222:223], v217 offset:0x1200
	ds_read_b64_tr_b16 v[224:225], v217 offset:0x1a00
	v_mfma_f32_32x32x16_bf16 v[114:129], v[226:229], v[138:141], v[114:129]
	ds_read_b64_tr_b16 v[226:227], v217 offset:0x2200
	ds_read_b64_tr_b16 v[228:229], v217 offset:0x2a00
	v_mfma_f32_32x32x16_bf16 v[114:129], v[230:233], v[142:145], v[114:129]
	ds_read_b64_tr_b16 v[230:231], v217 offset:0x3200
	ds_read_b64_tr_b16 v[232:233], v217 offset:0x3a00
	s_branch .Lattn_pvb2_2

; #define SBAR() __builtin_amdgcn_sched_barrier(0)
; #define SWRITE(b, S) do { *(bf16x8*)(V_lds + (b) * SHM_V + vst0) = vs##S##0; *(bf16x8*)(V_lds + (b) * SHM_V + vst1) = vs##S##1; \
;     *(bf16x8*)(K_lds + (b) * SHM_K + kst) = ks##S; } while (0)
; #define SWAIT() asm volatile("s_waitcnt vmcnt(3)" ::: "memory")
; __device__ __forceinline__ void pv_d0(f32x16* o, int vb, bf16x8 pa0, bf16x8 pa1, bf16x8 pa2, bf16x8 pa3) {
;   s16x4 va[8], vc[8];
;   pv_rd<0>(va, vb);
;   pv_rd<1>(vc, vb);
;   asm volatile("s_waitcnt lgkmcnt(8)" ::: "memory"); SBAR(); pv_mm(o[0], va, pa0, pa1, pa2, pa3); SBAR();
;   pv_rd<2>(va, vb); asm volatile("s_waitcnt lgkmcnt(8)" ::: "memory"); SBAR(); pv_mm(o[1], vc, pa0, pa1, pa2, pa3); SBAR();
;   pv_rd<3>(vc, vb); asm volatile("s_waitcnt lgkmcnt(8)" ::: "memory"); SBAR(); pv_mm(o[2], va, pa0, pa1, pa2, pa3); SBAR();
;   asm volatile("s_waitcnt lgkmcnt(0)" ::: "memory"); SBAR(); pv_mm(o[3], vc, pa0, pa1, pa2, pa3);
; }
; __device__ __forceinline__ void attn_stream(const u16* __restrict__ Qb, const u16* __restrict__ Kh, const u16* __restrict__ Vh,
;                                             int seq, char* lds, f32x16 (&o)[4]) {
;     ...
;     if (j + 3 < NT) { SWAIT(); SWRITE(b0, B); }
.Lattn_pvb2_2:
	s_waitcnt lgkmcnt(8)
	v_mfma_f32_32x32x16_bf16 v[2:17], v[170:173], v[98:101], v[2:17]
	ds_read_b64_tr_b16 v[98:99], v217 offset:0x400
	ds_read_b64_tr_b16 v[100:101], v217 offset:0xc00
	v_mfma_f32_32x32x16_bf16 v[2:17], v[174:177], v[102:105], v[2:17]
	ds_read_b64_tr_b16 v[102:103], v217 offset:0x1400
	ds_read_b64_tr_b16 v[104:105], v217 offset:0x1c00
	v_mfma_f32_32x32x16_bf16 v[2:17], v[178:181], v[106:109], v[2:17]
	ds_read_b64_tr_b16 v[106:107], v217 offset:0x2400
	ds_read_b64_tr_b16 v[108:109], v217 offset:0x2c00
	v_mfma_f32_32x32x16_bf16 v[2:17], v[182:185], v[110:113], v[2:17]
	ds_read_b64_tr_b16 v[110:111], v217 offset:0x3400
	ds_read_b64_tr_b16 v[112:113], v217 offset:0x3c00
	s_waitcnt vmcnt(3)
	s_cmp_lt_u32 s38, 64
	s_cbranch_scc1 .Lattn_oddw_2
	s_waitcnt vmcnt(0)
.Lattn_oddw_2:
	s_add_i32 s98, s43, 0
	v_add_u32_e32 v252, s98, v205
	v_lshl_add_u32 v254, s42, 13, v207
	v_add_u32_e32 v253, s98, v206
	s_waitcnt lgkmcnt(8)
	v_mfma_f32_32x32x16_bf16 v[50:65], v[170:173], v[218:221], v[50:65]
	ds_read_b64_tr_b16 v[218:219], v217 offset:0x600
	ds_read_b64_tr_b16 v[220:221], v217 offset:0xe00
	ds_write_b128 v252, v[154:157]
	v_mfma_f32_32x32x16_bf16 v[50:65], v[174:177], v[222:225], v[50:65]
	ds_read_b64_tr_b16 v[222:223], v217 offset:0x1600
	ds_read_b64_tr_b16 v[224:225], v217 offset:0x1e00
	ds_write_b128 v253, v[162:165]
	v_mfma_f32_32x32x16_bf16 v[50:65], v[178:181], v[226:229], v[50:65]
	ds_read_b64_tr_b16 v[226:227], v217 offset:0x2600
	ds_read_b64_tr_b16 v[228:229], v217 offset:0x2e00
	ds_write_b128 v254, v[166:169] offset:49152
	v_mfma_f32_32x32x16_bf16 v[50:65], v[182:185], v[230:233], v[50:65]
	ds_read_b64_tr_b16 v[230:231], v217 offset:0x3600
	ds_read_b64_tr_b16 v[232:233], v217 offset:0x3e00
	s_waitcnt lgkmcnt(11)
	v_mfma_f32_32x32x16_bf16 v[34:49], v[170:173], v[98:101], v[34:49]
	v_mfma_f32_32x32x16_bf16 v[34:49], v[174:177], v[102:105], v[34:49]
	v_mfma_f32_32x32x16_bf16 v[34:49], v[178:181], v[106:109], v[34:49]
	v_mfma_f32_32x32x16_bf16 v[34:49], v[182:185], v[110:113], v[34:49]
	s_waitcnt lgkmcnt(0)
	v_mfma_f32_32x32x16_bf16 v[18:33], v[170:173], v[218:221], v[18:33]
	v_mfma_f32_32x32x16_bf16 v[18:33], v[174:177], v[222:225], v[18:33]
	v_mfma_f32_32x32x16_bf16 v[18:33], v[178:181], v[226:229], v[18:33]
	v_mfma_f32_32x32x16_bf16 v[18:33], v[182:185], v[230:233], v[18:33]
	s_waitcnt lgkmcnt(0)
	s_barrier
	s_cmp_gt_u32 s38, 62
	s_cbranch_scc1 .LBB0_387
	v_add_co_u32_e32 v98, vcc, 0x20cd8000, v200
	s_nop 1
	v_addc_co_u32_e32 v99, vcc, 0, v201, vcc
	v_add_co_u32_e32 v100, vcc, 0x20ce8000, v200
	s_nop 1
	v_addc_co_u32_e32 v101, vcc, 0, v201, vcc
	global_load_dwordx4 v[154:157], v[98:99], off offset:256
	global_load_dwordx4 v[162:165], v[100:101], off offset:256
	v_add_co_u32_e32 v98, vcc, 0x1c8d8000, v198
	s_nop 1
	v_addc_co_u32_e32 v99, vcc, 0, v199, vcc
	global_load_dwordx4 v[166:169], v[98:99], off offset:384

; #define SBAR() __builtin_amdgcn_sched_barrier(0)
; __device__ __forceinline__ void attn_stream(const u16* __restrict__ Qb, const u16* __restrict__ Kh, const u16* __restrict__ Vh,
;                                             int seq, char* lds, f32x16 (&o)[4]) {
;     ...
;     SBAR(); __syncthreads(); SBAR();
;     t3 = b2;
.LBB0_395:
	s_add_i32 s38, s38, 2
	s_lshl_b32 s98, s42, 13
	v_add_u32_e32 v252, s98, v208
	v_add_u32_e32 v253, s98, v209
	v_add_u32_e32 v254, s98, v210
	v_add_u32_e32 v255, s98, v211
	ds_read_b128 v[236:239], v252 offset:49152
	ds_read_b128 v[240:243], v253 offset:49152
	ds_read_b128 v[244:247], v254 offset:49152
	ds_read_b128 v[248:251], v255 offset:49152
	v_lshl_add_u32 v226, s39, 14, v213
	s_barrier
	v_lshl_add_u64 v[194:195], v[194:195], 0, s[12:13]
	v_lshl_add_u64 v[196:197], v[196:197], 0, s[12:13]
	s_and_b64 vcc, exec, s[30:31]
	s_cbranch_vccnz .LBB0_399
	s_mov_b32 s42, s39
	s_branch .LBB0_371

; __device__ __forceinline__ int opq(int x) { asm volatile("" : "+v"(x)); return x; }
; __device__ __forceinline__ int crow(int r, int hi) { return (r & 3) + 8 * (r >> 2) + 4 * hi; }
; __device__ __forceinline__ void attn_stream(const u16* __restrict__ Qb, const u16* __restrict__ Kh, const u16* __restrict__ Vh,
;                                             int seq, char* lds, f32x16 (&o)[4]) {
;     ...
;   if (hi == 0) li_l[r32] = l_reg;
;   asm volatile("s_waitcnt lgkmcnt(0)" ::: "memory");
; #pragma unroll
;   for (int r = 0; r < 16; ++r) { const float rl = __builtin_amdgcn_rcpf(li_l[crow(r, hi)]);
; #pragma unroll
;     for (int d0 = 0; d0 < 4; ++d0) o[d0][r] *= rl; }
; __device__ __forceinline__ void phase3(const Params& p, char* shm) {
;     ...
;     const int tid = opq((int)threadIdx.x), wid = tid >> 6, lane = tid & 63, r32 = lane & 31, hi = lane >> 5;
;     { const f32x4* o1p = reinterpret_cast<const f32x4*>(o1s + tid * 64);
; #pragma unroll
;       for (int d0 = 0; d0 < 4; ++d0)
; #pragma unroll
;         for (int q = 0; q < 4; ++q) { const f32x4 v1 = o1p[d0 * 4 + q];
; #pragma unroll
;           for (int e = 0; e < 4; ++e) o[d0][q * 4 + e] = v1[e] - lam * o[d0][q * 4 + e]; } }
;     float sw[4];
; #pragma unroll
;     for (int d0 = 0; d0 < 4; ++d0) sw[d0] = p.subln[d0 * 32 + r32] * 0.8f;
;     char* const otb = shm + ((wid * 32 + 4 * hi) * OT_LD + r32) * 2;
; #pragma unroll
;     for (int r = 0; r < 16; ++r) {
;       float ss = 0.f;
; #pragma unroll
;       for (int d0 = 0; d0 < 4; ++d0) ss += o[d0][r] * o[d0][r];
;       ss += __shfl_xor(ss, 1); ss += __shfl_xor(ss, 2); ss += __shfl_xor(ss, 4); ss += __shfl_xor(ss, 8); ss += __shfl_xor(ss, 16);
;       const float rstd = rsqrtf(ss * (1.f / 128.f) + 1e-6f);
.LBB0_401:
	s_or_b64 exec, exec, s[6:7]
	s_and_saveexec_b64 s[0:1], s[4:5]
	ds_write_b32 v212, v192
	s_or_b64 exec, exec, s[0:1]
	s_waitcnt lgkmcnt(0)
	v_add_u32_e32 v66, v204, v190
	v_mov_b32_e32 v131, v1
	ds_read_b128 v[138:141], v66
	s_waitcnt vmcnt(2)
	ds_read_b128 v[144:147], v66 offset:32
	s_waitcnt vmcnt(1)
	ds_read_b128 v[148:151], v66 offset:64
	ds_read_b128 v[152:155], v66 offset:96
	s_waitcnt lgkmcnt(0)
	s_barrier
	v_mov_b32_e32 v156, v2
	v_lshlrev_b32_e32 v66, 6, v131
	v_ashrrev_i32_e32 v67, 31, v66
	v_lshl_add_u64 v[86:87], v[66:67], 2, s[16:17]
	global_load_dwordx4 v[118:121], v[86:87], off
	global_load_dwordx4 v[126:129], v[86:87], off offset:64
	global_load_dwordx4 v[114:117], v[86:87], off offset:128
	global_load_dwordx4 v[122:125], v[86:87], off offset:192
	global_load_dwordx4 v[110:113], v[86:87], off offset:16
	global_load_dwordx4 v[106:109], v[86:87], off offset:80
	global_load_dwordx4 v[102:105], v[86:87], off offset:144
	global_load_dwordx4 v[98:101], v[86:87], off offset:208
	v_and_b32_e32 v143, 31, v131
	v_lshlrev_b32_e32 v68, 2, v143
	global_load_dword v161, v68, s[14:15]
	global_load_dword v163, v68, s[14:15] offset:128
	v_and_b32_e32 v67, 64, v203
	v_xor_b32_e32 v66, 1, v203
	v_add_u32_e32 v2, 64, v67
	v_xor_b32_e32 v69, 2, v203
	v_cmp_lt_i32_e32 vcc, v66, v2
	v_xor_b32_e32 v70, 4, v203
	s_waitcnt vmcnt(10)
	v_mov_b32_e32 v159, v18
	v_mov_b32_e32 v18, v35
	v_cndmask_b32_e32 v35, v203, v66, vcc
	v_cmp_lt_i32_e32 vcc, v69, v2
	global_load_dword v165, v68, s[14:15] offset:256
	global_load_dword v168, v68, s[14:15] offset:384
	v_xor_b32_e32 v68, 8, v203
	v_cndmask_b32_e32 v66, v203, v69, vcc
	v_cmp_lt_i32_e32 vcc, v70, v2
	v_xor_b32_e32 v71, 16, v203
	v_mov_b32_e32 v157, v50
	v_cndmask_b32_e32 v67, v203, v70, vcc
	v_cmp_lt_i32_e32 vcc, v68, v2
	v_mov_b32_e32 v50, v3
	v_lshrrev_b32_e32 v3, 3, v131
	v_cndmask_b32_e32 v68, v203, v68, vcc
	v_cmp_lt_i32_e32 vcc, v71, v2
	v_mov_b32_e32 v158, v34
	v_lshrrev_b32_e32 v34, 1, v131
	v_cndmask_b32_e32 v2, v203, v71, vcc
	v_and_b32_e32 v69, 4, v3
	v_lshlrev_b32_e32 v3, 2, v2
	v_and_or_b32 v2, v34, s69, v69
	v_mul_lo_u32 v169, v2, s70
	v_rcp_f32_e32 v2, v138
	v_rcp_f32_e32 v162, v140
	v_rcp_f32_e32 v140, v146
	v_rcp_f32_e32 v138, v147
	v_pk_mul_f32 v[146:147], v[156:157], v[2:3] op_sel_hi:[1,0]
	v_pk_mul_f32 v[156:157], v[158:159], v[2:3] op_sel_hi:[1,0]
	v_lshlrev_b32_e32 v137, 2, v35
	v_lshlrev_b32_e32 v135, 2, v66
	v_lshlrev_b32_e32 v133, 2, v67
	v_lshlrev_b32_e32 v35, 2, v68
	v_rcp_f32_e32 v164, v141
	v_rcp_f32_e32 v160, v139
	v_or_b32_e32 v139, v169, v143
	v_rcp_f32_e32 v136, v148
	v_rcp_f32_e32 v134, v149
	v_rcp_f32_e32 v132, v150
	v_rcp_f32_e32 v130, v151
	global_load_dwordx4 v[74:77], v[86:87], off offset:48
	global_load_dwordx4 v[90:93], v[86:87], off offset:32
	global_load_dwordx4 v[78:81], v[86:87], off offset:112
	global_load_dwordx4 v[94:97], v[86:87], off offset:96
	global_load_dwordx4 v[66:69], v[86:87], off offset:176
	global_load_dwordx4 v[82:85], v[86:87], off offset:160
	global_load_dwordx4 v[70:73], v[86:87], off offset:240
	s_nop 0
	global_load_dwordx4 v[86:89], v[86:87], off offset:224
	v_rcp_f32_e32 v144, v144
	v_rcp_f32_e32 v142, v145
	s_waitcnt vmcnt(19)
	v_mov_b32_e32 v158, v118
	s_waitcnt vmcnt(18)
	v_mov_b32_e32 v159, v126
	s_waitcnt vmcnt(17)
	v_mov_b32_e32 v166, v114
	s_waitcnt vmcnt(16)
	v_mov_b32_e32 v167, v122
	v_pk_fma_f32 v[146:147], v[188:189], v[146:147], v[158:159] neg_lo:[1,0,0] neg_hi:[1,0,0]
	v_pk_fma_f32 v[156:157], v[188:189], v[156:157], v[166:167] neg_lo:[1,0,0] neg_hi:[1,0,0]
	v_pk_mul_f32 v[158:159], v[146:147], v[146:147]
	v_pk_mul_f32 v[166:167], v[156:157], v[156:157]
	v_add_f32_e32 v2, v158, v159
	v_add_f32_e32 v2, v2, v166
	v_add_f32_e32 v2, v2, v167
	ds_bpermute_b32 v34, v137, v2
	s_waitcnt vmcnt(11)
	v_pk_mul_f32 v[148:149], v[50:51], v[160:161] op_sel_hi:[1,0]
	v_pk_mul_f32 v[150:151], v[18:19], v[160:161] op_sel_hi:[1,0]
	v_mul_f32_e32 v51, 0x3f4ccccd, v161
	v_rcp_f32_e32 v118, v152
	s_waitcnt lgkmcnt(0)
	v_add_f32_e32 v122, v2, v34
	ds_bpermute_b32 v126, v135, v122
	v_rcp_f32_e32 v114, v153
	v_mov_b32_e32 v152, v116
	v_mov_b32_e32 v153, v124
	s_waitcnt vmcnt(10)
	v_mul_f32_e32 v50, 0x3f4ccccd, v163
	s_waitcnt lgkmcnt(0)
	v_add_f32_e32 v122, v122, v126
	ds_bpermute_b32 v126, v133, v122
	s_waitcnt vmcnt(9)
	v_mul_f32_e32 v19, 0x3f4ccccd, v165
	s_waitcnt vmcnt(8)
	v_mul_f32_e32 v18, 0x3f4ccccd, v168
	v_mov_b32_e32 v124, v117
	v_mov_b32_e32 v117, v22
	s_waitcnt lgkmcnt(0)
	v_add_f32_e32 v141, v122, v126
	ds_bpermute_b32 v143, v35, v141
	v_mov_b32_e32 v122, v115
	v_mov_b32_e32 v126, v119
	v_pk_fma_f32 v[126:127], v[188:189], v[148:149], v[126:127] neg_lo:[1,0,0] neg_hi:[1,0,0]
	v_pk_fma_f32 v[122:123], v[188:189], v[150:151], v[122:123] neg_lo:[1,0,0] neg_hi:[1,0,0]
	s_waitcnt lgkmcnt(0)
	v_add_f32_e32 v115, v141, v143
	ds_bpermute_b32 v119, v3, v115
	v_pk_mul_f32 v[148:149], v[126:127], v[126:127]
	v_pk_mul_f32 v[150:151], v[122:123], v[122:123]
	v_rcp_f32_e32 v34, v154
	v_rcp_f32_e32 v2, v155
	s_waitcnt lgkmcnt(0)
	v_add_f32_e32 v115, v115, v119
	v_add_f32_e32 v119, v148, v149
	v_add_f32_e32 v119, v119, v150
	v_add_f32_e32 v119, v119, v151
	v_fmamk_f32 v115, v115, 0x3c000000, v187
	ds_bpermute_b32 v141, v137, v119
	v_mul_f32_e32 v143, 0x4b800000, v115
	v_cmp_gt_f32_e32 vcc, s71, v115
	v_mov_b32_e32 v148, v120
	v_mov_b32_e32 v149, v128
	v_cndmask_b32_e32 v115, v115, v143, vcc
	v_rsq_f32_e32 v143, v115
	s_waitcnt lgkmcnt(0)
	v_add_f32_e32 v119, v119, v141
	ds_bpermute_b32 v141, v135, v119
	v_lshl_add_u32 v115, v139, 1, 0
	v_mul_f32_e32 v139, 0x45800000, v143
	v_cndmask_b32_e32 v139, v143, v139, vcc
	v_mul_f32_e32 v143, v146, v139
	v_mul_f32_e32 v143, v51, v143
	s_waitcnt lgkmcnt(0)
; __device__ __forceinline__ u16 f2bf(float f) { return (u16)(cvtpk(f, f) & 0xffffu); }
; __device__ __forceinline__ void phase3(const Params& p, char* shm) {
;     ...
;     char* const otb = shm + ((wid * 32 + 4 * hi) * OT_LD + r32) * 2;
; #pragma unroll
;     for (int r = 0; r < 16; ++r) {
;       float ss = 0.f;
; #pragma unroll
;       for (int d0 = 0; d0 < 4; ++d0) ss += o[d0][r] * o[d0][r];
;       ss += __shfl_xor(ss, 1); ss += __shfl_xor(ss, 2); ss += __shfl_xor(ss, 4); ss += __shfl_xor(ss, 8); ss += __shfl_xor(ss, 16);
;       const float rstd = rsqrtf(ss * (1.f / 128.f) + 1e-6f);
; #pragma unroll
;       for (int d0 = 0; d0 < 4; ++d0) *(u16*)(otb + (((r & 3) + 8 * (r >> 2)) * OT_LD + d0 * 32) * 2) = f2bf(o[d0][r] * rstd * sw[d0]);
;     }
	v_add_f32_e32 v119, v119, v141
	s_nop 0
	v_cvt_pk_bf16_f32 v143, v143, v143
	ds_bpermute_b32 v141, v133, v119
	ds_write_b16 v115, v143
	v_mul_f32_e32 v143, v147, v139
	v_mov_b32_e32 v146, v4
	v_mov_b32_e32 v147, v52
	v_pk_mul_f32 v[146:147], v[146:147], v[162:163] op_sel_hi:[1,0]
	v_mov_b32_e32 v150, v36
	v_mov_b32_e32 v151, v20
	v_pk_fma_f32 v[146:147], v[188:189], v[146:147], v[148:149] neg_lo:[1,0,0] neg_hi:[1,0,0]
	v_pk_mul_f32 v[150:151], v[150:151], v[162:163] op_sel_hi:[1,0]
	v_pk_mul_f32 v[148:149], v[146:147], v[146:147]
	v_pk_fma_f32 v[150:151], v[188:189], v[150:151], v[152:153] neg_lo:[1,0,0] neg_hi:[1,0,0]
	v_add_f32_e32 v4, v148, v149
	v_pk_mul_f32 v[152:153], v[150:151], v[150:151]
	s_waitcnt lgkmcnt(1)
	v_add_f32_e32 v119, v119, v141
	v_add_f32_e32 v4, v4, v152
	ds_bpermute_b32 v141, v35, v119
	v_add_f32_e32 v4, v4, v153
	ds_bpermute_b32 v20, v137, v4
	v_mul_f32_e32 v143, v50, v143
	s_nop 0
	v_cvt_pk_bf16_f32 v143, v143, v143
	s_waitcnt lgkmcnt(1)
	v_add_f32_e32 v119, v119, v141
	ds_bpermute_b32 v141, v3, v119
	s_waitcnt lgkmcnt(1)
	v_add_f32_e32 v4, v4, v20
	ds_bpermute_b32 v20, v135, v4
	ds_write_b16 v115, v143 offset:64
	v_mul_f32_e32 v143, v156, v139
	s_waitcnt lgkmcnt(2)
	v_add_f32_e32 v119, v119, v141
	v_fmamk_f32 v119, v119, 0x3c000000, v187
	s_waitcnt lgkmcnt(1)
	v_add_f32_e32 v4, v4, v20
	v_mul_f32_e32 v141, 0x4b800000, v119
	v_cmp_gt_f32_e32 vcc, s71, v119
	ds_bpermute_b32 v20, v133, v4
	v_mul_f32_e32 v139, v157, v139
	v_cndmask_b32_e32 v119, v119, v141, vcc
	v_rsq_f32_e32 v119, v119
	v_mul_f32_e32 v143, v19, v143
	v_mul_f32_e32 v36, v18, v139
	s_nop 0
	v_cvt_pk_bf16_f32 v143, v143, v143
	ds_write_b16 v115, v143 offset:128
	s_nop 0
	v_cvt_pk_bf16_f32 v36, v36, v36
	s_waitcnt lgkmcnt(1)
	v_add_f32_e32 v4, v4, v20
	ds_write_b16 v115, v36 offset:192
	v_mul_f32_e32 v36, 0x45800000, v119
	ds_bpermute_b32 v20, v35, v4
	v_cndmask_b32_e32 v36, v119, v36, vcc
	v_mul_f32_e32 v52, v126, v36
	v_mul_f32_e32 v52, v51, v52
	s_nop 0
	v_cvt_pk_bf16_f32 v52, v52, v52
	ds_write_b16 v115, v52 offset:272
	v_mul_f32_e32 v52, v127, v36
	s_waitcnt lgkmcnt(1)
	v_add_f32_e32 v4, v4, v20
	v_mul_f32_e32 v52, v50, v52
	ds_bpermute_b32 v20, v3, v4
	s_nop 0
	v_cvt_pk_bf16_f32 v52, v52, v52
	ds_write_b16 v115, v52 offset:336
	v_mul_f32_e32 v52, v122, v36
	v_mul_f32_e32 v52, v19, v52
	s_nop 0
	v_cvt_pk_bf16_f32 v52, v52, v52
	ds_write_b16 v115, v52 offset:400
	s_waitcnt lgkmcnt(2)
	v_add_f32_e32 v4, v4, v20
	v_mov_b32_e32 v52, v5
	v_fmamk_f32 v119, v4, 0x3c000000, v187
	v_pk_mul_f32 v[4:5], v[52:53], v[164:165] op_sel_hi:[1,0]
	v_mov_b32_e32 v128, v121
	v_mov_b32_e32 v20, v37
	v_mul_f32_e32 v36, v123, v36
	v_pk_fma_f32 v[4:5], v[188:189], v[4:5], v[128:129] neg_lo:[1,0,0] neg_hi:[1,0,0]
	v_pk_mul_f32 v[20:21], v[20:21], v[164:165] op_sel_hi:[1,0]
	v_mul_f32_e32 v36, v18, v36
	v_pk_mul_f32 v[52:53], v[4:5], v[4:5]
	v_pk_fma_f32 v[20:21], v[188:189], v[20:21], v[124:125] neg_lo:[1,0,0] neg_hi:[1,0,0]
	s_nop 0
	v_cvt_pk_bf16_f32 v116, v36, v36
	v_add_f32_e32 v52, v52, v53
	v_pk_mul_f32 v[36:37], v[20:21], v[20:21]
	v_cmp_gt_f32_e32 vcc, s71, v119
	v_add_f32_e32 v36, v52, v36
	v_add_f32_e32 v36, v36, v37
	ds_bpermute_b32 v37, v137, v36
	v_mul_f32_e32 v52, 0x4b800000, v119
	v_cndmask_b32_e32 v52, v119, v52, vcc
	v_rsq_f32_e32 v52, v52
	ds_write_b16 v115, v116 offset:464
	s_waitcnt lgkmcnt(1)
	v_add_f32_e32 v36, v36, v37
	ds_bpermute_b32 v37, v135, v36
	v_mul_f32_e32 v53, 0x45800000, v52
	v_cndmask_b32_e32 v52, v52, v53, vcc
	v_mul_f32_e32 v53, v146, v52
	v_mul_f32_e32 v53, v51, v53
	s_waitcnt lgkmcnt(0)
	v_add_f32_e32 v36, v36, v37
	ds_bpermute_b32 v37, v133, v36
	s_nop 0
	v_cvt_pk_bf16_f32 v53, v53, v53
	ds_write_b16 v115, v53 offset:544
	v_mul_f32_e32 v53, v147, v52
	v_mul_f32_e32 v53, v50, v53
	s_waitcnt lgkmcnt(1)
	v_add_f32_e32 v36, v36, v37
	ds_bpermute_b32 v37, v35, v36
	s_nop 0
	v_cvt_pk_bf16_f32 v53, v53, v53
	ds_write_b16 v115, v53 offset:608
	v_mul_f32_e32 v53, v150, v52
	v_mul_f32_e32 v53, v19, v53
	s_waitcnt lgkmcnt(1)
	v_add_f32_e32 v36, v36, v37
	ds_bpermute_b32 v37, v3, v36
	s_nop 0
	v_cvt_pk_bf16_f32 v53, v53, v53
	ds_write_b16 v115, v53 offset:672
	v_mul_f32_e32 v119, v151, v52
	v_mov_b32_e32 v52, v110
	s_waitcnt lgkmcnt(1)
	v_add_f32_e32 v36, v36, v37
	v_fmamk_f32 v36, v36, 0x3c000000, v187
	v_mul_f32_e32 v37, 0x4b800000, v36
	v_cmp_gt_f32_e32 vcc, s71, v36
	v_mov_b32_e32 v53, v106
	v_mov_b32_e32 v116, v38
	v_cndmask_b32_e32 v36, v36, v37, vcc
	v_rsq_f32_e32 v122, v36
	v_mov_b32_e32 v36, v6
	v_mov_b32_e32 v37, v54
	v_pk_mul_f32 v[36:37], v[36:37], v[144:145] op_sel_hi:[1,0]
	v_pk_mul_f32 v[116:117], v[116:117], v[144:145] op_sel_hi:[1,0]
	v_pk_fma_f32 v[36:37], v[188:189], v[36:37], v[52:53] neg_lo:[1,0,0] neg_hi:[1,0,0]
	v_mov_b32_e32 v120, v102
	v_mov_b32_e32 v121, v98
	v_pk_mul_f32 v[52:53], v[36:37], v[36:37]
	v_pk_fma_f32 v[116:117], v[188:189], v[116:117], v[120:121] neg_lo:[1,0,0] neg_hi:[1,0,0]
	v_add_f32_e32 v6, v52, v53
	v_pk_mul_f32 v[120:121], v[116:117], v[116:117]
	v_mul_f32_e32 v38, v18, v119
	v_add_f32_e32 v6, v6, v120
	v_add_f32_e32 v6, v6, v121
	ds_bpermute_b32 v22, v137, v6
	s_nop 0
	v_cvt_pk_bf16_f32 v38, v38, v38
	ds_write_b16 v115, v38 offset:736
	v_mul_f32_e32 v38, 0x45800000, v122
	v_cndmask_b32_e32 v38, v122, v38, vcc
	s_waitcnt lgkmcnt(1)
	v_add_f32_e32 v6, v6, v22
	ds_bpermute_b32 v22, v135, v6
	v_mul_f32_e32 v4, v4, v38
	v_mul_f32_e32 v4, v51, v4
	s_nop 0
	v_cvt_pk_bf16_f32 v4, v4, v4
	ds_write_b16 v115, v4 offset:816
	s_waitcnt lgkmcnt(1)
	v_add_f32_e32 v6, v6, v22
	ds_bpermute_b32 v22, v133, v6
	v_mul_f32_e32 v4, v5, v38
	v_mul_f32_e32 v4, v50, v4
	s_nop 0
	v_cvt_pk_bf16_f32 v4, v4, v4
	ds_write_b16 v115, v4 offset:880
	s_waitcnt lgkmcnt(1)
; __device__ __forceinline__ u16 f2bf(float f) { return (u16)(cvtpk(f, f) & 0xffffu); }
; __device__ __forceinline__ void phase3(const Params& p, char* shm) {
;     ...
;     char* const otb = shm + ((wid * 32 + 4 * hi) * OT_LD + r32) * 2;
; #pragma unroll
;     for (int r = 0; r < 16; ++r) {
;       float ss = 0.f;
; #pragma unroll
;       for (int d0 = 0; d0 < 4; ++d0) ss += o[d0][r] * o[d0][r];
;       ss += __shfl_xor(ss, 1); ss += __shfl_xor(ss, 2); ss += __shfl_xor(ss, 4); ss += __shfl_xor(ss, 8); ss += __shfl_xor(ss, 16);
;       const float rstd = rsqrtf(ss * (1.f / 128.f) + 1e-6f);
; #pragma unroll
;       for (int d0 = 0; d0 < 4; ++d0) *(u16*)(otb + (((r & 3) + 8 * (r >> 2)) * OT_LD + d0 * 32) * 2) = f2bf(o[d0][r] * rstd * sw[d0]);
;     }
	v_add_f32_e32 v5, v6, v22
	ds_bpermute_b32 v6, v35, v5
	v_mul_f32_e32 v4, v20, v38
	v_mul_f32_e32 v4, v19, v4
	s_nop 0
	v_cvt_pk_bf16_f32 v4, v4, v4
	ds_write_b16 v115, v4 offset:944
	s_waitcnt lgkmcnt(1)
	v_add_f32_e32 v5, v5, v6
	ds_bpermute_b32 v6, v3, v5
	v_mul_f32_e32 v4, v21, v38
	v_mul_f32_e32 v4, v18, v4
	s_nop 0
	v_cvt_pk_bf16_f32 v38, v4, v4
	v_mov_b32_e32 v54, v7
	s_waitcnt lgkmcnt(0)
	v_add_f32_e32 v4, v5, v6
	v_fmamk_f32 v52, v4, 0x3c000000, v187
	v_pk_mul_f32 v[4:5], v[54:55], v[142:143] op_sel_hi:[1,0]
	v_mov_b32_e32 v106, v111
	v_mov_b32_e32 v22, v39
	v_pk_fma_f32 v[4:5], v[188:189], v[4:5], v[106:107] neg_lo:[1,0,0] neg_hi:[1,0,0]
	v_pk_mul_f32 v[20:21], v[22:23], v[142:143] op_sel_hi:[1,0]
	v_mov_b32_e32 v98, v103
	v_pk_mul_f32 v[6:7], v[4:5], v[4:5]
	v_pk_fma_f32 v[20:21], v[188:189], v[20:21], v[98:99] neg_lo:[1,0,0] neg_hi:[1,0,0]
	v_add_f32_e32 v6, v6, v7
	v_pk_mul_f32 v[22:23], v[20:21], v[20:21]
	v_cmp_gt_f32_e32 vcc, s71, v52
	v_add_f32_e32 v6, v6, v22
	v_add_f32_e32 v6, v6, v23
	ds_bpermute_b32 v7, v137, v6
	v_mul_f32_e32 v22, 0x4b800000, v52
	v_cndmask_b32_e32 v22, v52, v22, vcc
	v_rsq_f32_e32 v22, v22
	ds_write_b16 v115, v38 offset:1008
	s_waitcnt lgkmcnt(1)
	v_add_f32_e32 v6, v6, v7
	ds_bpermute_b32 v7, v135, v6
	v_mul_f32_e32 v23, 0x45800000, v22
	v_cndmask_b32_e32 v22, v22, v23, vcc
	v_mul_f32_e32 v23, v36, v22
	v_mul_f32_e32 v23, v51, v23
	s_waitcnt lgkmcnt(0)
	v_add_f32_e32 v6, v6, v7
	ds_bpermute_b32 v7, v133, v6
	s_nop 0
	v_cvt_pk_bf16_f32 v23, v23, v23
	ds_write_b16 v115, v23 offset:2176
	v_mul_f32_e32 v23, v37, v22
	v_mul_f32_e32 v23, v50, v23
	s_waitcnt lgkmcnt(1)
	v_add_f32_e32 v6, v6, v7
	ds_bpermute_b32 v7, v35, v6
	s_nop 0
	v_cvt_pk_bf16_f32 v23, v23, v23
	ds_write_b16 v115, v23 offset:2240
	v_mul_f32_e32 v23, v116, v22
	v_mul_f32_e32 v23, v19, v23
	s_waitcnt lgkmcnt(1)
	v_add_f32_e32 v6, v6, v7
	ds_bpermute_b32 v7, v3, v6
	s_nop 0
	v_cvt_pk_bf16_f32 v23, v23, v23
	ds_write_b16 v115, v23 offset:2304
	v_mul_f32_e32 v52, v117, v22
	v_mov_b32_e32 v22, v112
	s_waitcnt lgkmcnt(1)
	v_add_f32_e32 v6, v6, v7
	v_fmamk_f32 v6, v6, 0x3c000000, v187
	v_mul_f32_e32 v7, 0x4b800000, v6
	v_cmp_gt_f32_e32 vcc, s71, v6
	v_mov_b32_e32 v23, v108
	v_mov_b32_e32 v36, v40
	v_cndmask_b32_e32 v6, v6, v7, vcc
	v_rsq_f32_e32 v53, v6
	v_mov_b32_e32 v6, v8
	v_mov_b32_e32 v7, v56
	v_pk_mul_f32 v[6:7], v[6:7], v[140:141] op_sel_hi:[1,0]
	v_mov_b32_e32 v37, v24
	v_pk_fma_f32 v[6:7], v[188:189], v[6:7], v[22:23] neg_lo:[1,0,0] neg_hi:[1,0,0]
	v_pk_mul_f32 v[36:37], v[36:37], v[140:141] op_sel_hi:[1,0]
	v_mov_b32_e32 v38, v104
	v_mov_b32_e32 v39, v100
	v_pk_mul_f32 v[22:23], v[6:7], v[6:7]
	v_pk_fma_f32 v[36:37], v[188:189], v[36:37], v[38:39] neg_lo:[1,0,0] neg_hi:[1,0,0]
	v_add_f32_e32 v8, v22, v23
	v_pk_mul_f32 v[38:39], v[36:37], v[36:37]
	v_mul_f32_e32 v23, v18, v52
	v_add_f32_e32 v8, v8, v38
	v_add_f32_e32 v8, v8, v39
	ds_bpermute_b32 v22, v137, v8
	s_nop 0
	v_cvt_pk_bf16_f32 v23, v23, v23
	ds_write_b16 v115, v23 offset:2368
	v_mul_f32_e32 v23, 0x45800000, v53
	v_cndmask_b32_e32 v23, v53, v23, vcc
	s_waitcnt lgkmcnt(1)
	v_add_f32_e32 v8, v8, v22
	ds_bpermute_b32 v22, v135, v8
	v_mul_f32_e32 v4, v4, v23
	v_mul_f32_e32 v4, v51, v4
	s_nop 0
	v_cvt_pk_bf16_f32 v4, v4, v4
	ds_write_b16 v115, v4 offset:2448
	s_waitcnt lgkmcnt(1)
	v_add_f32_e32 v8, v8, v22
	ds_bpermute_b32 v22, v133, v8
	v_mul_f32_e32 v4, v5, v23
	v_mul_f32_e32 v4, v50, v4
	s_nop 0
	v_cvt_pk_bf16_f32 v4, v4, v4
	ds_write_b16 v115, v4 offset:2512
	s_waitcnt lgkmcnt(1)
	v_add_f32_e32 v5, v8, v22
	ds_bpermute_b32 v8, v35, v5
	v_mul_f32_e32 v4, v20, v23
	v_mul_f32_e32 v4, v19, v4
	s_nop 0
	v_cvt_pk_bf16_f32 v4, v4, v4
	ds_write_b16 v115, v4 offset:2576
	s_waitcnt lgkmcnt(1)
	v_add_f32_e32 v5, v5, v8
	ds_bpermute_b32 v8, v3, v5
	v_mul_f32_e32 v4, v21, v23
	v_mul_f32_e32 v4, v18, v4
	s_nop 0
	v_cvt_pk_bf16_f32 v38, v4, v4
	v_mov_b32_e32 v56, v9
	s_waitcnt lgkmcnt(0)
	v_add_f32_e32 v4, v5, v8
	v_fmamk_f32 v39, v4, 0x3c000000, v187
	v_pk_mul_f32 v[4:5], v[56:57], v[138:139] op_sel_hi:[1,0]
	v_mov_b32_e32 v108, v113
	v_mov_b32_e32 v24, v41
	v_pk_fma_f32 v[4:5], v[188:189], v[4:5], v[108:109] neg_lo:[1,0,0] neg_hi:[1,0,0]
	v_pk_mul_f32 v[20:21], v[24:25], v[138:139] op_sel_hi:[1,0]
	v_mov_b32_e32 v100, v105
	v_pk_mul_f32 v[8:9], v[4:5], v[4:5]
	v_pk_fma_f32 v[20:21], v[188:189], v[20:21], v[100:101] neg_lo:[1,0,0] neg_hi:[1,0,0]
	v_add_f32_e32 v8, v8, v9
	v_pk_mul_f32 v[22:23], v[20:21], v[20:21]
	v_cmp_gt_f32_e32 vcc, s71, v39
	v_add_f32_e32 v8, v8, v22
	v_add_f32_e32 v8, v8, v23
	ds_bpermute_b32 v9, v137, v8
	v_mul_f32_e32 v22, 0x4b800000, v39
	v_cndmask_b32_e32 v22, v39, v22, vcc
	v_rsq_f32_e32 v22, v22
	ds_write_b16 v115, v38 offset:2640
	s_waitcnt lgkmcnt(1)
	v_add_f32_e32 v8, v8, v9
	ds_bpermute_b32 v9, v135, v8
	v_mul_f32_e32 v23, 0x45800000, v22
	v_cndmask_b32_e32 v22, v22, v23, vcc
	v_mul_f32_e32 v6, v6, v22
	v_mul_f32_e32 v6, v51, v6
	s_waitcnt lgkmcnt(0)
	v_add_f32_e32 v8, v8, v9
	ds_bpermute_b32 v9, v133, v8
	s_nop 0
	v_cvt_pk_bf16_f32 v6, v6, v6
	ds_write_b16 v115, v6 offset:2720
	v_mul_f32_e32 v6, v7, v22
	v_mul_f32_e32 v6, v50, v6
	s_waitcnt lgkmcnt(1)
	v_add_f32_e32 v7, v8, v9
	ds_bpermute_b32 v8, v35, v7
	s_nop 0
	v_cvt_pk_bf16_f32 v6, v6, v6
	ds_write_b16 v115, v6 offset:2784
	v_mul_f32_e32 v6, v36, v22
	v_mul_f32_e32 v6, v19, v6
	s_waitcnt lgkmcnt(1)
	v_add_f32_e32 v7, v7, v8
	ds_bpermute_b32 v8, v3, v7
	s_nop 0
	v_cvt_pk_bf16_f32 v6, v6, v6
	ds_write_b16 v115, v6 offset:2848
	v_mul_f32_e32 v36, v37, v22
	s_waitcnt vmcnt(4)
	v_mov_b32_e32 v9, v94
	s_waitcnt lgkmcnt(1)
; __device__ __forceinline__ u16 f2bf(float f) { return (u16)(cvtpk(f, f) & 0xffffu); }
; __device__ __forceinline__ void phase3(const Params& p, char* shm) {
;     ...
;     char* const otb = shm + ((wid * 32 + 4 * hi) * OT_LD + r32) * 2;
; #pragma unroll
;     for (int r = 0; r < 16; ++r) {
;       float ss = 0.f;
; #pragma unroll
;       for (int d0 = 0; d0 < 4; ++d0) ss += o[d0][r] * o[d0][r];
;       ss += __shfl_xor(ss, 1); ss += __shfl_xor(ss, 2); ss += __shfl_xor(ss, 4); ss += __shfl_xor(ss, 8); ss += __shfl_xor(ss, 16);
;       const float rstd = rsqrtf(ss * (1.f / 128.f) + 1e-6f);
; #pragma unroll
;       for (int d0 = 0; d0 < 4; ++d0) *(u16*)(otb + (((r & 3) + 8 * (r >> 2)) * OT_LD + d0 * 32) * 2) = f2bf(o[d0][r] * rstd * sw[d0]);
;     }
	v_add_f32_e32 v6, v7, v8
	v_fmamk_f32 v6, v6, 0x3c000000, v187
	v_mul_f32_e32 v7, 0x4b800000, v6
	v_cmp_gt_f32_e32 vcc, s71, v6
	v_mov_b32_e32 v8, v90
	v_mov_b32_e32 v22, v42
	v_cndmask_b32_e32 v6, v6, v7, vcc
	v_rsq_f32_e32 v37, v6
	v_mov_b32_e32 v6, v10
	v_mov_b32_e32 v7, v58
	v_pk_mul_f32 v[6:7], v[6:7], v[136:137] op_sel_hi:[1,0]
	v_mov_b32_e32 v23, v26
	v_pk_fma_f32 v[6:7], v[188:189], v[6:7], v[8:9] neg_lo:[1,0,0] neg_hi:[1,0,0]
	v_pk_mul_f32 v[22:23], v[22:23], v[136:137] op_sel_hi:[1,0]
	s_waitcnt vmcnt(2)
	v_mov_b32_e32 v24, v82
	s_waitcnt vmcnt(0)
	v_mov_b32_e32 v25, v86
	v_pk_mul_f32 v[8:9], v[6:7], v[6:7]
	v_pk_fma_f32 v[22:23], v[188:189], v[22:23], v[24:25] neg_lo:[1,0,0] neg_hi:[1,0,0]
	v_add_f32_e32 v8, v8, v9
	v_pk_mul_f32 v[24:25], v[22:23], v[22:23]
	v_mul_f32_e32 v10, v18, v36
	v_add_f32_e32 v8, v8, v24
	v_add_f32_e32 v8, v8, v25
	ds_bpermute_b32 v9, v137, v8
	s_nop 0
	v_cvt_pk_bf16_f32 v10, v10, v10
	ds_write_b16 v115, v10 offset:2912
	v_mul_f32_e32 v10, 0x45800000, v37
	v_cndmask_b32_e32 v10, v37, v10, vcc
	s_waitcnt lgkmcnt(1)
	v_add_f32_e32 v8, v8, v9
	ds_bpermute_b32 v9, v135, v8
	v_mul_f32_e32 v4, v4, v10
	v_mul_f32_e32 v4, v51, v4
	s_nop 0
	v_cvt_pk_bf16_f32 v4, v4, v4
	ds_write_b16 v115, v4 offset:2992
	s_waitcnt lgkmcnt(1)
	v_add_f32_e32 v8, v8, v9
	ds_bpermute_b32 v9, v133, v8
	v_mul_f32_e32 v4, v5, v10
	v_mul_f32_e32 v4, v50, v4
	s_nop 0
	v_cvt_pk_bf16_f32 v4, v4, v4
	ds_write_b16 v115, v4 offset:3056
	s_waitcnt lgkmcnt(1)
	v_add_f32_e32 v5, v8, v9
	ds_bpermute_b32 v8, v35, v5
	v_mul_f32_e32 v4, v20, v10
	v_mul_f32_e32 v4, v19, v4
	s_nop 0
	v_cvt_pk_bf16_f32 v4, v4, v4
	ds_write_b16 v115, v4 offset:3120
	s_waitcnt lgkmcnt(1)
	v_add_f32_e32 v5, v5, v8
	ds_bpermute_b32 v8, v3, v5
	v_mul_f32_e32 v4, v21, v10
	v_mul_f32_e32 v4, v18, v4
	s_nop 0
	v_cvt_pk_bf16_f32 v24, v4, v4
	v_mov_b32_e32 v58, v11
	s_waitcnt lgkmcnt(0)
	v_add_f32_e32 v4, v5, v8
	v_fmamk_f32 v25, v4, 0x3c000000, v187
	v_pk_mul_f32 v[4:5], v[58:59], v[134:135] op_sel_hi:[1,0]
	v_mov_b32_e32 v94, v91
	v_mov_b32_e32 v26, v43
	v_pk_fma_f32 v[4:5], v[188:189], v[4:5], v[94:95] neg_lo:[1,0,0] neg_hi:[1,0,0]
	v_pk_mul_f32 v[10:11], v[26:27], v[134:135] op_sel_hi:[1,0]
	v_mov_b32_e32 v86, v83
	v_pk_mul_f32 v[8:9], v[4:5], v[4:5]
	v_pk_fma_f32 v[10:11], v[188:189], v[10:11], v[86:87] neg_lo:[1,0,0] neg_hi:[1,0,0]
	v_add_f32_e32 v8, v8, v9
	v_pk_mul_f32 v[20:21], v[10:11], v[10:11]
	v_cmp_gt_f32_e32 vcc, s71, v25
	v_add_f32_e32 v8, v8, v20
	v_add_f32_e32 v8, v8, v21
	ds_bpermute_b32 v9, v137, v8
	v_mul_f32_e32 v20, 0x4b800000, v25
	v_cndmask_b32_e32 v20, v25, v20, vcc
	v_rsq_f32_e32 v20, v20
	ds_write_b16 v115, v24 offset:3184
	s_waitcnt lgkmcnt(1)
	v_add_f32_e32 v8, v8, v9
	ds_bpermute_b32 v9, v135, v8
	v_mul_f32_e32 v21, 0x45800000, v20
	v_cndmask_b32_e32 v20, v20, v21, vcc
	v_mul_f32_e32 v6, v6, v20
	v_mul_f32_e32 v6, v51, v6
	s_waitcnt lgkmcnt(0)
	v_add_f32_e32 v8, v8, v9
	ds_bpermute_b32 v9, v133, v8
	s_nop 0
	v_cvt_pk_bf16_f32 v6, v6, v6
	ds_write_b16 v115, v6 offset:4352
	v_mul_f32_e32 v6, v7, v20
	v_mul_f32_e32 v6, v50, v6
	s_waitcnt lgkmcnt(1)
	v_add_f32_e32 v7, v8, v9
	ds_bpermute_b32 v8, v35, v7
	s_nop 0
	v_cvt_pk_bf16_f32 v6, v6, v6
	ds_write_b16 v115, v6 offset:4416
	v_mul_f32_e32 v6, v22, v20
	v_mul_f32_e32 v6, v19, v6
	s_waitcnt lgkmcnt(1)
	v_add_f32_e32 v7, v7, v8
	ds_bpermute_b32 v8, v3, v7
	s_nop 0
	v_cvt_pk_bf16_f32 v6, v6, v6
	ds_write_b16 v115, v6 offset:4480
	v_mul_f32_e32 v24, v23, v20
	v_mov_b32_e32 v9, v96
	s_waitcnt lgkmcnt(1)
	v_add_f32_e32 v6, v7, v8
	v_fmamk_f32 v6, v6, 0x3c000000, v187
	v_mul_f32_e32 v7, 0x4b800000, v6
	v_cmp_gt_f32_e32 vcc, s71, v6
	v_mov_b32_e32 v8, v92
	v_mov_b32_e32 v20, v44
	v_cndmask_b32_e32 v6, v6, v7, vcc
	v_rsq_f32_e32 v25, v6
	v_mov_b32_e32 v6, v12
	v_mov_b32_e32 v7, v60
	v_pk_mul_f32 v[6:7], v[6:7], v[132:133] op_sel_hi:[1,0]
	v_mov_b32_e32 v21, v28
	v_pk_fma_f32 v[6:7], v[188:189], v[6:7], v[8:9] neg_lo:[1,0,0] neg_hi:[1,0,0]
	v_pk_mul_f32 v[20:21], v[20:21], v[132:133] op_sel_hi:[1,0]
	v_mov_b32_e32 v22, v84
	v_mov_b32_e32 v23, v88
	v_pk_mul_f32 v[8:9], v[6:7], v[6:7]
	v_pk_fma_f32 v[20:21], v[188:189], v[20:21], v[22:23] neg_lo:[1,0,0] neg_hi:[1,0,0]
	v_add_f32_e32 v8, v8, v9
	v_pk_mul_f32 v[22:23], v[20:21], v[20:21]
	v_mul_f32_e32 v12, v18, v24
	v_add_f32_e32 v8, v8, v22
	v_add_f32_e32 v8, v8, v23
	ds_bpermute_b32 v9, v137, v8
	s_nop 0
	v_cvt_pk_bf16_f32 v12, v12, v12
	ds_write_b16 v115, v12 offset:4544
	v_mul_f32_e32 v12, 0x45800000, v25
	v_cndmask_b32_e32 v12, v25, v12, vcc
	s_waitcnt lgkmcnt(1)
	v_add_f32_e32 v8, v8, v9
	ds_bpermute_b32 v9, v135, v8
	v_mul_f32_e32 v4, v4, v12
	v_mul_f32_e32 v4, v51, v4
	s_nop 0
	v_cvt_pk_bf16_f32 v4, v4, v4
	ds_write_b16 v115, v4 offset:4624
	s_waitcnt lgkmcnt(1)
	v_add_f32_e32 v8, v8, v9
	ds_bpermute_b32 v9, v133, v8
	v_mul_f32_e32 v4, v5, v12
	v_mul_f32_e32 v4, v50, v4
	s_nop 0
	v_cvt_pk_bf16_f32 v4, v4, v4
	ds_write_b16 v115, v4 offset:4688
	s_waitcnt lgkmcnt(1)
	v_add_f32_e32 v5, v8, v9
	ds_bpermute_b32 v8, v35, v5
	v_mul_f32_e32 v4, v10, v12
	v_mul_f32_e32 v4, v19, v4
	s_nop 0
	v_cvt_pk_bf16_f32 v4, v4, v4
	ds_write_b16 v115, v4 offset:4752
	s_waitcnt lgkmcnt(1)
	v_add_f32_e32 v5, v5, v8
	ds_bpermute_b32 v8, v3, v5
	v_mul_f32_e32 v4, v11, v12
	v_mul_f32_e32 v4, v18, v4
	s_nop 0
	v_cvt_pk_bf16_f32 v22, v4, v4
	v_mov_b32_e32 v60, v13
	s_waitcnt lgkmcnt(0)
; __device__ __forceinline__ u16 f2bf(float f) { return (u16)(cvtpk(f, f) & 0xffffu); }
; __device__ __forceinline__ void phase3(const Params& p, char* shm) {
;     ...
;     char* const otb = shm + ((wid * 32 + 4 * hi) * OT_LD + r32) * 2;
; #pragma unroll
;     for (int r = 0; r < 16; ++r) {
;       float ss = 0.f;
; #pragma unroll
;       for (int d0 = 0; d0 < 4; ++d0) ss += o[d0][r] * o[d0][r];
;       ss += __shfl_xor(ss, 1); ss += __shfl_xor(ss, 2); ss += __shfl_xor(ss, 4); ss += __shfl_xor(ss, 8); ss += __shfl_xor(ss, 16);
;       const float rstd = rsqrtf(ss * (1.f / 128.f) + 1e-6f);
; #pragma unroll
;       for (int d0 = 0; d0 < 4; ++d0) *(u16*)(otb + (((r & 3) + 8 * (r >> 2)) * OT_LD + d0 * 32) * 2) = f2bf(o[d0][r] * rstd * sw[d0]);
;     }
	v_add_f32_e32 v4, v5, v8
	v_fmamk_f32 v23, v4, 0x3c000000, v187
	v_pk_mul_f32 v[4:5], v[60:61], v[130:131] op_sel_hi:[1,0]
	v_mov_b32_e32 v96, v93
	v_mov_b32_e32 v28, v45
	v_pk_fma_f32 v[4:5], v[188:189], v[4:5], v[96:97] neg_lo:[1,0,0] neg_hi:[1,0,0]
	v_pk_mul_f32 v[10:11], v[28:29], v[130:131] op_sel_hi:[1,0]
	v_mov_b32_e32 v88, v85
	v_pk_mul_f32 v[8:9], v[4:5], v[4:5]
	v_pk_fma_f32 v[10:11], v[188:189], v[10:11], v[88:89] neg_lo:[1,0,0] neg_hi:[1,0,0]
	v_add_f32_e32 v8, v8, v9
	v_pk_mul_f32 v[12:13], v[10:11], v[10:11]
	v_cmp_gt_f32_e32 vcc, s71, v23
	v_add_f32_e32 v8, v8, v12
	v_add_f32_e32 v8, v8, v13
	ds_bpermute_b32 v9, v137, v8
	v_mul_f32_e32 v12, 0x4b800000, v23
	v_cndmask_b32_e32 v12, v23, v12, vcc
	v_rsq_f32_e32 v12, v12
	ds_write_b16 v115, v22 offset:4816
	s_waitcnt lgkmcnt(1)
	v_add_f32_e32 v8, v8, v9
	ds_bpermute_b32 v9, v135, v8
	v_mul_f32_e32 v13, 0x45800000, v12
	v_cndmask_b32_e32 v12, v12, v13, vcc
	v_mul_f32_e32 v6, v6, v12
	v_mul_f32_e32 v6, v51, v6
	s_waitcnt lgkmcnt(0)
	v_add_f32_e32 v8, v8, v9
	ds_bpermute_b32 v9, v133, v8
	s_nop 0
	v_cvt_pk_bf16_f32 v6, v6, v6
	ds_write_b16 v115, v6 offset:4896
	v_mul_f32_e32 v6, v7, v12
	v_mul_f32_e32 v6, v50, v6
	s_waitcnt lgkmcnt(1)
	v_add_f32_e32 v7, v8, v9
	ds_bpermute_b32 v8, v35, v7
	s_nop 0
	v_cvt_pk_bf16_f32 v6, v6, v6
	ds_write_b16 v115, v6 offset:4960
	v_mul_f32_e32 v6, v20, v12
	v_mul_f32_e32 v6, v19, v6
	s_waitcnt lgkmcnt(1)
	v_add_f32_e32 v7, v7, v8
	ds_bpermute_b32 v8, v3, v7
	s_nop 0
	v_cvt_pk_bf16_f32 v6, v6, v6
	ds_write_b16 v115, v6 offset:5024
	v_mul_f32_e32 v22, v21, v12
	v_mov_b32_e32 v9, v78
	s_waitcnt lgkmcnt(1)
	v_add_f32_e32 v6, v7, v8
	v_fmamk_f32 v6, v6, 0x3c000000, v187
	v_mul_f32_e32 v7, 0x4b800000, v6
	v_cmp_gt_f32_e32 vcc, s71, v6
	v_mov_b32_e32 v8, v74
	v_mov_b32_e32 v12, v46
	v_cndmask_b32_e32 v6, v6, v7, vcc
	v_rsq_f32_e32 v23, v6
	v_mov_b32_e32 v6, v14
	v_mov_b32_e32 v7, v62
	v_pk_mul_f32 v[6:7], v[6:7], v[118:119] op_sel_hi:[1,0]
	v_mov_b32_e32 v13, v30
	v_pk_fma_f32 v[6:7], v[188:189], v[6:7], v[8:9] neg_lo:[1,0,0] neg_hi:[1,0,0]
	v_pk_mul_f32 v[12:13], v[12:13], v[118:119] op_sel_hi:[1,0]
	v_mov_b32_e32 v20, v66
	v_mov_b32_e32 v21, v70
	v_pk_mul_f32 v[8:9], v[6:7], v[6:7]
	v_pk_fma_f32 v[12:13], v[188:189], v[12:13], v[20:21] neg_lo:[1,0,0] neg_hi:[1,0,0]
	v_add_f32_e32 v8, v8, v9
	v_pk_mul_f32 v[20:21], v[12:13], v[12:13]
	v_mul_f32_e32 v14, v18, v22
	v_add_f32_e32 v8, v8, v20
	v_add_f32_e32 v8, v8, v21
	ds_bpermute_b32 v9, v137, v8
	s_nop 0
	v_cvt_pk_bf16_f32 v14, v14, v14
	ds_write_b16 v115, v14 offset:5088
	v_mul_f32_e32 v14, 0x45800000, v23
	v_cndmask_b32_e32 v14, v23, v14, vcc
	s_waitcnt lgkmcnt(1)
	v_add_f32_e32 v8, v8, v9
	ds_bpermute_b32 v9, v135, v8
	v_mul_f32_e32 v4, v4, v14
	v_mul_f32_e32 v4, v51, v4
	s_nop 0
	v_cvt_pk_bf16_f32 v4, v4, v4
	ds_write_b16 v115, v4 offset:5168
	s_waitcnt lgkmcnt(1)
	v_add_f32_e32 v8, v8, v9
	ds_bpermute_b32 v9, v133, v8
	v_mul_f32_e32 v4, v5, v14
	v_mul_f32_e32 v4, v50, v4
	s_nop 0
	v_cvt_pk_bf16_f32 v4, v4, v4
	ds_write_b16 v115, v4 offset:5232
	s_waitcnt lgkmcnt(1)
	v_add_f32_e32 v5, v8, v9
	ds_bpermute_b32 v8, v35, v5
	v_mul_f32_e32 v4, v10, v14
	v_mul_f32_e32 v4, v19, v4
	s_nop 0
	v_cvt_pk_bf16_f32 v4, v4, v4
	ds_write_b16 v115, v4 offset:5296
	s_waitcnt lgkmcnt(1)
	v_add_f32_e32 v5, v5, v8
	ds_bpermute_b32 v8, v3, v5
	v_mul_f32_e32 v4, v11, v14
	v_mul_f32_e32 v4, v18, v4
	s_nop 0
	v_cvt_pk_bf16_f32 v20, v4, v4
	v_mov_b32_e32 v62, v15
	s_waitcnt lgkmcnt(0)
	v_add_f32_e32 v4, v5, v8
	v_fmamk_f32 v21, v4, 0x3c000000, v187
	v_pk_mul_f32 v[4:5], v[62:63], v[114:115] op_sel_hi:[1,0]
	v_mov_b32_e32 v78, v75
	v_mov_b32_e32 v30, v47
	v_pk_fma_f32 v[4:5], v[188:189], v[4:5], v[78:79] neg_lo:[1,0,0] neg_hi:[1,0,0]
	v_pk_mul_f32 v[10:11], v[30:31], v[114:115] op_sel_hi:[1,0]
	v_mov_b32_e32 v70, v67
	v_pk_mul_f32 v[8:9], v[4:5], v[4:5]
	v_pk_fma_f32 v[10:11], v[188:189], v[10:11], v[70:71] neg_lo:[1,0,0] neg_hi:[1,0,0]
	v_add_f32_e32 v8, v8, v9
	v_pk_mul_f32 v[14:15], v[10:11], v[10:11]
	v_cmp_gt_f32_e32 vcc, s71, v21
	v_add_f32_e32 v8, v8, v14
	v_add_f32_e32 v8, v8, v15
	ds_bpermute_b32 v9, v137, v8
	v_mul_f32_e32 v14, 0x4b800000, v21
	v_cndmask_b32_e32 v14, v21, v14, vcc
	v_rsq_f32_e32 v14, v14
	ds_write_b16 v115, v20 offset:5360
	s_waitcnt lgkmcnt(1)
	v_add_f32_e32 v8, v8, v9
	ds_bpermute_b32 v9, v135, v8
	v_mul_f32_e32 v15, 0x45800000, v14
	v_cndmask_b32_e32 v14, v14, v15, vcc
	v_mul_f32_e32 v6, v6, v14
	v_mul_f32_e32 v6, v51, v6
	s_waitcnt lgkmcnt(0)
	v_add_f32_e32 v8, v8, v9
	ds_bpermute_b32 v9, v133, v8
	s_nop 0
	v_cvt_pk_bf16_f32 v6, v6, v6
	ds_write_b16 v115, v6 offset:6528
	v_mul_f32_e32 v6, v7, v14
	v_mul_f32_e32 v6, v50, v6
	s_waitcnt lgkmcnt(1)
	v_add_f32_e32 v7, v8, v9
	ds_bpermute_b32 v8, v35, v7
	s_nop 0
	v_cvt_pk_bf16_f32 v6, v6, v6
	ds_write_b16 v115, v6 offset:6592
	v_mul_f32_e32 v6, v12, v14
	v_mul_f32_e32 v6, v19, v6
	s_waitcnt lgkmcnt(1)
	v_add_f32_e32 v7, v7, v8
	ds_bpermute_b32 v8, v3, v7
	s_nop 0
	v_cvt_pk_bf16_f32 v6, v6, v6
	ds_write_b16 v115, v6 offset:6656
	v_mul_f32_e32 v20, v13, v14
	v_mov_b32_e32 v9, v80
	s_waitcnt lgkmcnt(1)
	v_add_f32_e32 v6, v7, v8
	v_fmamk_f32 v6, v6, 0x3c000000, v187
	v_mul_f32_e32 v7, 0x4b800000, v6
	v_cmp_gt_f32_e32 vcc, s71, v6
	v_mov_b32_e32 v8, v76
	v_mov_b32_e32 v12, v48
	v_cndmask_b32_e32 v6, v6, v7, vcc
	v_rsq_f32_e32 v21, v6
	v_mov_b32_e32 v6, v16
	v_mov_b32_e32 v7, v64
	v_pk_mul_f32 v[6:7], v[6:7], v[34:35] op_sel_hi:[1,0]
	v_mov_b32_e32 v13, v32
	v_pk_fma_f32 v[6:7], v[188:189], v[6:7], v[8:9] neg_lo:[1,0,0] neg_hi:[1,0,0]
	v_pk_mul_f32 v[12:13], v[12:13], v[34:35] op_sel_hi:[1,0]
	v_mov_b32_e32 v14, v68
	v_mov_b32_e32 v15, v72
	v_pk_mul_f32 v[8:9], v[6:7], v[6:7]
	v_pk_fma_f32 v[12:13], v[188:189], v[12:13], v[14:15] neg_lo:[1,0,0] neg_hi:[1,0,0]
	v_add_f32_e32 v8, v8, v9
	v_pk_mul_f32 v[14:15], v[12:13], v[12:13]
	v_mov_b32_e32 v64, v17
	v_add_f32_e32 v8, v8, v14
	v_add_f32_e32 v8, v8, v15
	ds_bpermute_b32 v9, v137, v8
	v_mul_f32_e32 v14, v18, v20
	s_nop 0
	v_cvt_pk_bf16_f32 v14, v14, v14
	ds_write_b16 v115, v14 offset:6720
	v_mul_f32_e32 v14, 0x45800000, v21
	s_waitcnt lgkmcnt(1)
; __device__ __forceinline__ float bflo(unsigned v) { return __uint_as_float(v << 16); }
; __device__ __forceinline__ float bfhi(unsigned v) { return __uint_as_float(v & 0xffff0000u); }
; __device__ __forceinline__ void phase3(const Params& p, char* shm) {
;     ...
;     { const u16* zsrc = Zb + t0 * AW + h * 128; u16* bdst = Bin + t0 * AW + h * 128;
; #pragma unroll 2
;       for (int id = tid; id < 256 * 16; id += NTHR) {
;         const int row = id >> 4, c = id & 15;
;         const u32x4 ov = *reinterpret_cast<const u32x4*>(shm + (row * OT_LD + c * 8) * 2);
;         const u32x4 zv = *reinterpret_cast<const u32x4*>(zsrc + (size_t)row * AW + c * 8);
;         u32x4 w;
; #pragma unroll
;         for (int q = 0; q < 4; ++q) w[q] = cvtpk(bflo(ov[q]) * bflo(zv[q]), bfhi(ov[q]) * bfhi(zv[q]));
;         *reinterpret_cast<u32x4*>(bdst + (size_t)row * AW + c * 8) = w;
;       }
	v_add_f32_e32 v8, v8, v9
	ds_bpermute_b32 v9, v135, v8
	v_cndmask_b32_e32 v14, v21, v14, vcc
	v_mul_f32_e32 v4, v4, v14
	v_mul_f32_e32 v4, v51, v4
	s_nop 0
	v_cvt_pk_bf16_f32 v4, v4, v4
	s_waitcnt lgkmcnt(0)
	v_add_f32_e32 v8, v8, v9
	ds_bpermute_b32 v9, v133, v8
	ds_write_b16 v115, v4 offset:6800
	v_mul_f32_e32 v4, v5, v14
	v_mul_f32_e32 v4, v50, v4
	s_nop 0
	v_cvt_pk_bf16_f32 v4, v4, v4
	s_waitcnt lgkmcnt(1)
	v_add_f32_e32 v5, v8, v9
	ds_bpermute_b32 v8, v35, v5
	ds_write_b16 v115, v4 offset:6864
	v_mul_f32_e32 v4, v10, v14
	v_mul_f32_e32 v4, v19, v4
	s_nop 0
	v_cvt_pk_bf16_f32 v4, v4, v4
	s_waitcnt lgkmcnt(1)
	v_add_f32_e32 v5, v5, v8
	ds_bpermute_b32 v8, v3, v5
	ds_write_b16 v115, v4 offset:6928
	v_mul_f32_e32 v4, v11, v14
	v_mul_f32_e32 v4, v18, v4
	s_nop 0
	v_cvt_pk_bf16_f32 v16, v4, v4
	s_waitcnt lgkmcnt(1)
	v_add_f32_e32 v4, v5, v8
	v_fmamk_f32 v20, v4, 0x3c000000, v187
	v_pk_mul_f32 v[4:5], v[64:65], v[2:3] op_sel_hi:[1,0]
	v_mov_b32_e32 v80, v77
	v_mov_b32_e32 v32, v49
	v_pk_fma_f32 v[4:5], v[188:189], v[4:5], v[80:81] neg_lo:[1,0,0] neg_hi:[1,0,0]
	v_pk_mul_f32 v[10:11], v[32:33], v[2:3] op_sel_hi:[1,0]
	v_mov_b32_e32 v72, v69
	v_pk_mul_f32 v[8:9], v[4:5], v[4:5]
	v_pk_fma_f32 v[10:11], v[188:189], v[10:11], v[72:73] neg_lo:[1,0,0] neg_hi:[1,0,0]
	v_add_f32_e32 v2, v8, v9
	v_pk_mul_f32 v[14:15], v[10:11], v[10:11]
	v_mul_f32_e32 v9, 0x4b800000, v20
	v_add_f32_e32 v2, v2, v14
	v_add_f32_e32 v2, v2, v15
	ds_bpermute_b32 v8, v137, v2
	v_cmp_gt_f32_e32 vcc, s71, v20
	ds_write_b16 v115, v16 offset:6992
	s_waitcnt lgkmcnt(1)
	v_add_f32_e32 v2, v2, v8
	ds_bpermute_b32 v8, v135, v2
	v_cndmask_b32_e32 v9, v20, v9, vcc
	v_rsq_f32_e32 v9, v9
	s_waitcnt lgkmcnt(0)
	v_add_f32_e32 v2, v2, v8
	ds_bpermute_b32 v8, v133, v2
	v_mul_f32_e32 v14, 0x45800000, v9
	v_cndmask_b32_e32 v9, v9, v14, vcc
	v_mul_f32_e32 v6, v6, v9
	v_mul_f32_e32 v6, v51, v6
	s_nop 0
	v_cvt_pk_bf16_f32 v6, v6, v6
	s_waitcnt lgkmcnt(0)
	v_add_f32_e32 v2, v2, v8
	ds_write_b16 v115, v6 offset:7072
	v_mul_f32_e32 v6, v7, v9
	ds_bpermute_b32 v7, v35, v2
	v_mul_f32_e32 v6, v50, v6
	s_nop 0
	v_cvt_pk_bf16_f32 v6, v6, v6
	ds_write_b16 v115, v6 offset:7136
	v_mul_f32_e32 v6, v12, v9
	s_waitcnt lgkmcnt(1)
	v_add_f32_e32 v2, v2, v7
	ds_bpermute_b32 v3, v3, v2
	v_mul_f32_e32 v6, v19, v6
	s_nop 0
	v_cvt_pk_bf16_f32 v6, v6, v6
	ds_write_b16 v115, v6 offset:7200
	v_mul_f32_e32 v6, v13, v9
	s_waitcnt lgkmcnt(1)
	v_add_f32_e32 v2, v2, v3
	v_fmamk_f32 v2, v2, 0x3c000000, v187
	v_mul_f32_e32 v3, 0x4b800000, v2
	v_cmp_gt_f32_e32 vcc, s71, v2
	s_nop 1
	v_cndmask_b32_e32 v2, v2, v3, vcc
	v_rsq_f32_e32 v2, v2
	v_mul_f32_e32 v3, v18, v6
	s_nop 0
	v_cvt_pk_bf16_f32 v3, v3, v3
	ds_write_b16 v115, v3 offset:7264
	v_mul_f32_e32 v3, 0x45800000, v2
	v_cndmask_b32_e32 v2, v2, v3, vcc
	v_mul_f32_e32 v3, v4, v2
	v_mul_f32_e32 v3, v51, v3
	s_nop 0
	v_cvt_pk_bf16_f32 v3, v3, v3
	ds_write_b16 v115, v3 offset:7344
	v_mul_f32_e32 v3, v5, v2
	v_mul_f32_e32 v3, v50, v3
	s_nop 0
	v_cvt_pk_bf16_f32 v3, v3, v3
	ds_write_b16 v115, v3 offset:7408
	v_mul_f32_e32 v3, v10, v2
	v_mul_f32_e32 v2, v11, v2
	v_mul_f32_e32 v3, v19, v3
	v_mul_f32_e32 v2, v18, v2
	v_cmp_gt_i32_e32 vcc, s72, v131
	s_nop 0
	v_cvt_pk_bf16_f32 v3, v3, v3
	ds_write_b16 v115, v3 offset:7472
	s_nop 0
	v_cvt_pk_bf16_f32 v2, v2, v2
	ds_write_b16 v115, v2 offset:7536
	s_waitcnt lgkmcnt(0)
	s_barrier
	s_and_saveexec_b64 s[0:1], vcc
	s_cbranch_execz .LBB0_322
	s_add_u32 s4, s79, s18
	s_addc_u32 s5, s80, s19
	s_add_u32 s4, s4, s86
	s_addc_u32 s5, s5, 0
	s_add_u32 s6, s81, s18
	s_addc_u32 s7, s82, s19
	s_add_u32 s6, s6, s86
	s_addc_u32 s7, s7, 0
	v_lshlrev_b32_e32 v2, 3, v131
	v_lshrrev_b32_e32 v52, 4, v131
	v_and_b32_e32 v53, 15, v131
	v_lshlrev_b32_e32 v54, 11, v52
	v_lshl_add_u32 v54, v53, 4, v54
	v_mul_u32_u24_e32 v52, 0x110, v52
	v_lshl_add_u32 v52, v53, 4, v52
	v_add_u32_e32 v55, 0x10000, v54
	v_add_u32_e32 v56, 0x20000, v54
	v_add_u32_e32 v57, 0x30000, v54
	v_add_u32_e32 v58, 0x40000, v54
	v_add_u32_e32 v59, 0x50000, v54
	v_add_u32_e32 v60, 0x60000, v54
	v_add_u32_e32 v61, 0x70000, v54
	global_load_dwordx4 v[4:7], v54, s[4:5]
	global_load_dwordx4 v[8:11], v55, s[4:5]
	global_load_dwordx4 v[12:15], v56, s[4:5]
	global_load_dwordx4 v[16:19], v57, s[4:5]
	global_load_dwordx4 v[20:23], v58, s[4:5]
	global_load_dwordx4 v[24:27], v59, s[4:5]
	global_load_dwordx4 v[28:31], v60, s[4:5]
	global_load_dwordx4 v[32:35], v61, s[4:5]
	ds_read_b128 v[36:39], v52
	ds_read_b128 v[40:43], v52 offset:8704
	ds_read_b128 v[44:47], v52 offset:17408
	ds_read_b128 v[48:51], v52 offset:26112
	s_waitcnt vmcnt(7) lgkmcnt(3)
	v_lshlrev_b32_e32 v62, 16, v36
	v_lshlrev_b32_e32 v63, 16, v4
	v_and_b32_e32 v36, 0xffff0000, v36
	v_and_b32_e32 v4, 0xffff0000, v4
	v_mul_f32_e32 v62, v63, v62
	v_mul_f32_e32 v4, v4, v36
	v_cvt_pk_bf16_f32 v4, v62, v4
	v_lshlrev_b32_e32 v62, 16, v37
	v_lshlrev_b32_e32 v63, 16, v5
	v_and_b32_e32 v37, 0xffff0000, v37
	v_and_b32_e32 v5, 0xffff0000, v5
	v_mul_f32_e32 v62, v63, v62
	v_mul_f32_e32 v5, v5, v37
	v_cvt_pk_bf16_f32 v5, v62, v5
	v_lshlrev_b32_e32 v62, 16, v38
	v_lshlrev_b32_e32 v63, 16, v6
	v_and_b32_e32 v38, 0xffff0000, v38
	v_and_b32_e32 v6, 0xffff0000, v6
	v_mul_f32_e32 v62, v63, v62
	v_mul_f32_e32 v6, v6, v38
	v_cvt_pk_bf16_f32 v6, v62, v6
	v_lshlrev_b32_e32 v62, 16, v39
	v_lshlrev_b32_e32 v63, 16, v7
	v_and_b32_e32 v39, 0xffff0000, v39
	v_and_b32_e32 v7, 0xffff0000, v7
	v_mul_f32_e32 v62, v63, v62
	v_mul_f32_e32 v7, v7, v39
	v_cvt_pk_bf16_f32 v7, v62, v7
	global_store_dwordx4 v54, v[4:7], s[6:7]
	s_waitcnt vmcnt(7) lgkmcnt(2)
; __device__ __forceinline__ float bflo(unsigned v) { return __uint_as_float(v << 16); }
; __device__ __forceinline__ float bfhi(unsigned v) { return __uint_as_float(v & 0xffff0000u); }
; __device__ __forceinline__ void phase3(const Params& p, char* shm) {
;     ...
;     { const u16* zsrc = Zb + t0 * AW + h * 128; u16* bdst = Bin + t0 * AW + h * 128;
; #pragma unroll 2
;       for (int id = tid; id < 256 * 16; id += NTHR) {
;         const int row = id >> 4, c = id & 15;
;         const u32x4 ov = *reinterpret_cast<const u32x4*>(shm + (row * OT_LD + c * 8) * 2);
;         const u32x4 zv = *reinterpret_cast<const u32x4*>(zsrc + (size_t)row * AW + c * 8);
;         u32x4 w;
; #pragma unroll
;         for (int q = 0; q < 4; ++q) w[q] = cvtpk(bflo(ov[q]) * bflo(zv[q]), bfhi(ov[q]) * bfhi(zv[q]));
;         *reinterpret_cast<u32x4*>(bdst + (size_t)row * AW + c * 8) = w;
;       }
	v_lshlrev_b32_e32 v62, 16, v40
	v_lshlrev_b32_e32 v63, 16, v8
	v_and_b32_e32 v40, 0xffff0000, v40
	v_and_b32_e32 v8, 0xffff0000, v8
	v_mul_f32_e32 v62, v63, v62
	v_mul_f32_e32 v8, v8, v40
	v_cvt_pk_bf16_f32 v8, v62, v8
	v_lshlrev_b32_e32 v62, 16, v41
	v_lshlrev_b32_e32 v63, 16, v9
	v_and_b32_e32 v41, 0xffff0000, v41
	v_and_b32_e32 v9, 0xffff0000, v9
	v_mul_f32_e32 v62, v63, v62
	v_mul_f32_e32 v9, v9, v41
	v_cvt_pk_bf16_f32 v9, v62, v9
	v_lshlrev_b32_e32 v62, 16, v42
	v_lshlrev_b32_e32 v63, 16, v10
	v_and_b32_e32 v42, 0xffff0000, v42
	v_and_b32_e32 v10, 0xffff0000, v10
	v_mul_f32_e32 v62, v63, v62
	v_mul_f32_e32 v10, v10, v42
	v_cvt_pk_bf16_f32 v10, v62, v10
	v_lshlrev_b32_e32 v62, 16, v43
	v_lshlrev_b32_e32 v63, 16, v11
	v_and_b32_e32 v43, 0xffff0000, v43
	v_and_b32_e32 v11, 0xffff0000, v11
	v_mul_f32_e32 v62, v63, v62
	v_mul_f32_e32 v11, v11, v43
	v_cvt_pk_bf16_f32 v11, v62, v11
	global_store_dwordx4 v55, v[8:11], s[6:7]
	s_waitcnt vmcnt(7) lgkmcnt(1)
	v_lshlrev_b32_e32 v62, 16, v44
	v_lshlrev_b32_e32 v63, 16, v12
	v_and_b32_e32 v44, 0xffff0000, v44
	v_and_b32_e32 v12, 0xffff0000, v12
	v_mul_f32_e32 v62, v63, v62
	v_mul_f32_e32 v12, v12, v44
	v_cvt_pk_bf16_f32 v12, v62, v12
	v_lshlrev_b32_e32 v62, 16, v45
	v_lshlrev_b32_e32 v63, 16, v13
	v_and_b32_e32 v45, 0xffff0000, v45
	v_and_b32_e32 v13, 0xffff0000, v13
	v_mul_f32_e32 v62, v63, v62
	v_mul_f32_e32 v13, v13, v45
	v_cvt_pk_bf16_f32 v13, v62, v13
	v_lshlrev_b32_e32 v62, 16, v46
	v_lshlrev_b32_e32 v63, 16, v14
	v_and_b32_e32 v46, 0xffff0000, v46
	v_and_b32_e32 v14, 0xffff0000, v14
	v_mul_f32_e32 v62, v63, v62
	v_mul_f32_e32 v14, v14, v46
	v_cvt_pk_bf16_f32 v14, v62, v14
	v_lshlrev_b32_e32 v62, 16, v47
	v_lshlrev_b32_e32 v63, 16, v15
	v_and_b32_e32 v47, 0xffff0000, v47
	v_and_b32_e32 v15, 0xffff0000, v15
	v_mul_f32_e32 v62, v63, v62
	v_mul_f32_e32 v15, v15, v47
	v_cvt_pk_bf16_f32 v15, v62, v15
	global_store_dwordx4 v56, v[12:15], s[6:7]
	s_waitcnt vmcnt(7) lgkmcnt(0)
	v_lshlrev_b32_e32 v62, 16, v48
	v_lshlrev_b32_e32 v63, 16, v16
	v_and_b32_e32 v48, 0xffff0000, v48
	v_and_b32_e32 v16, 0xffff0000, v16
	v_mul_f32_e32 v62, v63, v62
	v_mul_f32_e32 v16, v16, v48
	v_cvt_pk_bf16_f32 v16, v62, v16
	v_lshlrev_b32_e32 v62, 16, v49
	v_lshlrev_b32_e32 v63, 16, v17
	v_and_b32_e32 v49, 0xffff0000, v49
	v_and_b32_e32 v17, 0xffff0000, v17
	v_mul_f32_e32 v62, v63, v62
	v_mul_f32_e32 v17, v17, v49
	v_cvt_pk_bf16_f32 v17, v62, v17
	v_lshlrev_b32_e32 v62, 16, v50
	v_lshlrev_b32_e32 v63, 16, v18
	v_and_b32_e32 v50, 0xffff0000, v50
	v_and_b32_e32 v18, 0xffff0000, v18
	v_mul_f32_e32 v62, v63, v62
	v_mul_f32_e32 v18, v18, v50
	v_cvt_pk_bf16_f32 v18, v62, v18
	v_lshlrev_b32_e32 v62, 16, v51
	v_lshlrev_b32_e32 v63, 16, v19
	v_and_b32_e32 v51, 0xffff0000, v51
	v_and_b32_e32 v19, 0xffff0000, v19
	v_mul_f32_e32 v62, v63, v62
	v_mul_f32_e32 v19, v19, v51
	v_cvt_pk_bf16_f32 v19, v62, v19
	global_store_dwordx4 v57, v[16:19], s[6:7]
	ds_read_b128 v[36:39], v52 offset:34816
	ds_read_b128 v[40:43], v52 offset:43520
	ds_read_b128 v[44:47], v52 offset:52224
	ds_read_b128 v[48:51], v52 offset:60928
	s_waitcnt vmcnt(7) lgkmcnt(3)
	v_lshlrev_b32_e32 v62, 16, v36
	v_lshlrev_b32_e32 v63, 16, v20
	v_and_b32_e32 v36, 0xffff0000, v36
	v_and_b32_e32 v20, 0xffff0000, v20
	v_mul_f32_e32 v62, v63, v62
	v_mul_f32_e32 v20, v20, v36
	v_cvt_pk_bf16_f32 v20, v62, v20
	v_lshlrev_b32_e32 v62, 16, v37
	v_lshlrev_b32_e32 v63, 16, v21
	v_and_b32_e32 v37, 0xffff0000, v37
	v_and_b32_e32 v21, 0xffff0000, v21
	v_mul_f32_e32 v62, v63, v62
	v_mul_f32_e32 v21, v21, v37
	v_cvt_pk_bf16_f32 v21, v62, v21
	v_lshlrev_b32_e32 v62, 16, v38
	v_lshlrev_b32_e32 v63, 16, v22
	v_and_b32_e32 v38, 0xffff0000, v38
	v_and_b32_e32 v22, 0xffff0000, v22
	v_mul_f32_e32 v62, v63, v62
	v_mul_f32_e32 v22, v22, v38
	v_cvt_pk_bf16_f32 v22, v62, v22
	v_lshlrev_b32_e32 v62, 16, v39
	v_lshlrev_b32_e32 v63, 16, v23
	v_and_b32_e32 v39, 0xffff0000, v39
	v_and_b32_e32 v23, 0xffff0000, v23
	v_mul_f32_e32 v62, v63, v62
	v_mul_f32_e32 v23, v23, v39
	v_cvt_pk_bf16_f32 v23, v62, v23
	global_store_dwordx4 v58, v[20:23], s[6:7]
	s_waitcnt vmcnt(7) lgkmcnt(2)
; __device__ __forceinline__ float bflo(unsigned v) { return __uint_as_float(v << 16); }
; __device__ __forceinline__ float bfhi(unsigned v) { return __uint_as_float(v & 0xffff0000u); }
; __device__ __forceinline__ void phase3(const Params& p, char* shm) {
;     ...
;     { const u16* zsrc = Zb + t0 * AW + h * 128; u16* bdst = Bin + t0 * AW + h * 128;
; #pragma unroll 2
;       for (int id = tid; id < 256 * 16; id += NTHR) {
;         const int row = id >> 4, c = id & 15;
;         const u32x4 ov = *reinterpret_cast<const u32x4*>(shm + (row * OT_LD + c * 8) * 2);
;         const u32x4 zv = *reinterpret_cast<const u32x4*>(zsrc + (size_t)row * AW + c * 8);
;         u32x4 w;
; #pragma unroll
;         for (int q = 0; q < 4; ++q) w[q] = cvtpk(bflo(ov[q]) * bflo(zv[q]), bfhi(ov[q]) * bfhi(zv[q]));
;         *reinterpret_cast<u32x4*>(bdst + (size_t)row * AW + c * 8) = w;
;       }
	v_lshlrev_b32_e32 v62, 16, v40
	v_lshlrev_b32_e32 v63, 16, v24
	v_and_b32_e32 v40, 0xffff0000, v40
	v_and_b32_e32 v24, 0xffff0000, v24
	v_mul_f32_e32 v62, v63, v62
	v_mul_f32_e32 v24, v24, v40
	v_cvt_pk_bf16_f32 v24, v62, v24
	v_lshlrev_b32_e32 v62, 16, v41
	v_lshlrev_b32_e32 v63, 16, v25
	v_and_b32_e32 v41, 0xffff0000, v41
	v_and_b32_e32 v25, 0xffff0000, v25
	v_mul_f32_e32 v62, v63, v62
	v_mul_f32_e32 v25, v25, v41
	v_cvt_pk_bf16_f32 v25, v62, v25
	v_lshlrev_b32_e32 v62, 16, v42
	v_lshlrev_b32_e32 v63, 16, v26
	v_and_b32_e32 v42, 0xffff0000, v42
	v_and_b32_e32 v26, 0xffff0000, v26
	v_mul_f32_e32 v62, v63, v62
	v_mul_f32_e32 v26, v26, v42
	v_cvt_pk_bf16_f32 v26, v62, v26
	v_lshlrev_b32_e32 v62, 16, v43
	v_lshlrev_b32_e32 v63, 16, v27
	v_and_b32_e32 v43, 0xffff0000, v43
	v_and_b32_e32 v27, 0xffff0000, v27
	v_mul_f32_e32 v62, v63, v62
	v_mul_f32_e32 v27, v27, v43
	v_cvt_pk_bf16_f32 v27, v62, v27
	global_store_dwordx4 v59, v[24:27], s[6:7]
	s_waitcnt vmcnt(7) lgkmcnt(1)
	v_lshlrev_b32_e32 v62, 16, v44
	v_lshlrev_b32_e32 v63, 16, v28
	v_and_b32_e32 v44, 0xffff0000, v44
	v_and_b32_e32 v28, 0xffff0000, v28
	v_mul_f32_e32 v62, v63, v62
	v_mul_f32_e32 v28, v28, v44
	v_cvt_pk_bf16_f32 v28, v62, v28
	v_lshlrev_b32_e32 v62, 16, v45
	v_lshlrev_b32_e32 v63, 16, v29
	v_and_b32_e32 v45, 0xffff0000, v45
	v_and_b32_e32 v29, 0xffff0000, v29
	v_mul_f32_e32 v62, v63, v62
	v_mul_f32_e32 v29, v29, v45
	v_cvt_pk_bf16_f32 v29, v62, v29
	v_lshlrev_b32_e32 v62, 16, v46
	v_lshlrev_b32_e32 v63, 16, v30
	v_and_b32_e32 v46, 0xffff0000, v46
	v_and_b32_e32 v30, 0xffff0000, v30
	v_mul_f32_e32 v62, v63, v62
	v_mul_f32_e32 v30, v30, v46
	v_cvt_pk_bf16_f32 v30, v62, v30
	v_lshlrev_b32_e32 v62, 16, v47
	v_lshlrev_b32_e32 v63, 16, v31
	v_and_b32_e32 v47, 0xffff0000, v47
	v_and_b32_e32 v31, 0xffff0000, v31
	v_mul_f32_e32 v62, v63, v62
	v_mul_f32_e32 v31, v31, v47
	v_cvt_pk_bf16_f32 v31, v62, v31
	global_store_dwordx4 v60, v[28:31], s[6:7]
	s_waitcnt vmcnt(7) lgkmcnt(0)
	v_lshlrev_b32_e32 v62, 16, v48
	v_lshlrev_b32_e32 v63, 16, v32
	v_and_b32_e32 v48, 0xffff0000, v48
	v_and_b32_e32 v32, 0xffff0000, v32
	v_mul_f32_e32 v62, v63, v62
	v_mul_f32_e32 v32, v32, v48
	v_cvt_pk_bf16_f32 v32, v62, v32
	v_lshlrev_b32_e32 v62, 16, v49
	v_lshlrev_b32_e32 v63, 16, v33
	v_and_b32_e32 v49, 0xffff0000, v49
	v_and_b32_e32 v33, 0xffff0000, v33
	v_mul_f32_e32 v62, v63, v62
	v_mul_f32_e32 v33, v33, v49
	v_cvt_pk_bf16_f32 v33, v62, v33
	v_lshlrev_b32_e32 v62, 16, v50
	v_lshlrev_b32_e32 v63, 16, v34
	v_and_b32_e32 v50, 0xffff0000, v50
	v_and_b32_e32 v34, 0xffff0000, v34
	v_mul_f32_e32 v62, v63, v62
	v_mul_f32_e32 v34, v34, v50
	v_cvt_pk_bf16_f32 v34, v62, v34
	v_lshlrev_b32_e32 v62, 16, v51
	v_lshlrev_b32_e32 v63, 16, v35
	v_and_b32_e32 v51, 0xffff0000, v51
	v_and_b32_e32 v35, 0xffff0000, v35
	v_mul_f32_e32 v62, v63, v62
	v_mul_f32_e32 v35, v35, v51
	v_cvt_pk_bf16_f32 v35, v62, v35
	global_store_dwordx4 v61, v[32:35], s[6:7]
	v_add_u32_e32 v131, 0x1000, v131
	v_and_b32_e32 v190, 0x78, v2
	v_lshlrev_b32_e32 v190, 1, v190
	v_add_u32_e32 v2, 0x8000, v2
	s_mov_b64 s[18:19], exec
	s_nop 1
	s_branch .LBB0_322
